# gemm_phase K-loops: first trip peeled with C=0 on the first MFMA of each accumulator; 128-instruction accumulator zeroing per unit removed (4 instances)
# speedup vs baseline: 1.0084x; 1.0045x over previous
; template <class Epi, class Sched>
; __device__ __forceinline__ void gemm_phase(LAS unsigned char* lds, const Gemm g, const Sched S, const Epi E, const int tid) {
;     ...
;     f32x4 acc[2][2][4][2];
; #pragma unroll
;     for (int a = 0; a < 2; ++a)
; #pragma unroll
;         for (int b = 0; b < 2; ++b)
; #pragma unroll
;             for (int m = 0; m < 4; ++m)
; #pragma unroll
;                 for (int n = 0; n < 2; ++n) acc[a][b][m][n] = (f32x4){0.f, 0.f, 0.f, 0.f};
;     bf16x8 At[4][2], B0[2][2], B1[2][2];
;     const char* cA = (const char*)g.A + (size_t)cur.pm * tstepA; const char* cB = (const char*)g.Bt + (size_t)cur.pn * tstepB;
;     PG8_STAGE(PG8_SB(0, 0), cB, voffB); PG8_STAGE(PG8_SB(0, 1), cB + hstepB, voffB); PG8_STAGE(PG8_SA(0, 0), cA, voffA); PG8_STAGE(PG8_SA(0, 1), cA + hstepA, voffA);
;     if (wr == 1) PG8_BAR;
;     PG8_WAIT_V(2); PG8_BAR;
;     PG8_STAGE(PG8_SB(1, 0), cB + kstep, voffB); PG8_STAGE(PG8_SA(1, 0), cA + kstep, voffA); PG8_STAGE(PG8_SB(1, 1), cB + hstepB + kstep, voffB);
;     PG8_WAIT_V(6); PG8_BAR;
;     for (;;) {
;         const bool has_next = S.next(ui + 1, nxt);
;         const char* nA = has_next ? (const char*)g.A + (size_t)nxt.pm * tstepA : cA; const char* nB = has_next ? (const char*)g.Bt + (size_t)nxt.pn * tstepB : cB;
;         for (int t = 0; t < nt; t += 2) {
;             const bool last = (t == nt - 2);
;             const char* a1 = cA + (size_t)(t + 1) * kstep;
;             const char* a2 = last ? nA : cA + (size_t)(t + 2) * kstep; const char* b2 = last ? nB : cB + (size_t)(t + 2) * kstep;
;             const char* a3 = a2 + kstep; const char* b3 = b2 + kstep;
;             PG8_LDB(B0, 0, 0); PG8_LDB(B1, 0, 1); PG8_SCHED; PG8_LDA(At, 0, 0); PG8_STAGE(PG8_SA(1, 1), a1 + hstepA, voffA);
;             PG8_WAIT_V(8); PG8_WAIT_L(0); PG8_BAR; PG8_MMA(0, 0, At, B0); PG8_MMA(0, 1, At, B1); PG8_BAR; PG8_SCHED;
;             PG8_LDA(At, 0, 1); PG8_STAGE(PG8_SB(0, 0), b2, voffB); PG8_STAGE(PG8_SB(0, 1), b2 + hstepB, voffB); PG8_STAGE(PG8_SA(0, 0), a2, voffA);
;             PG8_WAIT_V(8); PG8_WAIT_L(0); PG8_BAR; PG8_MMA(1, 0, At, B0); PG8_MMA(1, 1, At, B1); PG8_BAR; PG8_SCHED;
;             PG8_LDB(B0, 1, 0); PG8_LDB(B1, 1, 1); PG8_SCHED; PG8_LDA(At, 1, 0); PG8_STAGE(PG8_SA(0, 1), a2 + hstepA, voffA);
;             PG8_WAIT_V(8); PG8_WAIT_L(0); PG8_BAR; PG8_MMA(0, 0, At, B0); PG8_MMA(0, 1, At, B1); PG8_BAR; PG8_SCHED;
.LBB0_91:
	s_ashr_i32 s73, s72, 31
	s_lshl_b64 s[24:25], s[72:73], 19
	s_add_u32 s26, s3, s24
	s_addc_u32 s27, s14, s25
	s_ashr_i32 s71, s70, 31
	s_lshl_b64 s[24:25], s[70:71], 19
	v_readlane_b32 s40, v254, 44
	v_readlane_b32 s41, v254, 45
	s_add_u32 s74, s40, s24
	s_addc_u32 s75, s41, s25
	s_andn2_b64 vcc, exec, s[22:23]
	s_cbranch_vccnz .Lpl93_zero
	s_and_b64 s[24:25], s[4:5], exec
	s_cselect_b32 s7, s27, s21
	s_cselect_b32 s9, s26, s20
	s_cselect_b32 s35, s75, s11
	s_cselect_b32 s36, s74, s10
	s_add_u32 s37, s10, 0x100
	s_addc_u32 s38, s11, 0
	s_add_u32 s10, s20, 0x40080
	v_mov_b32_e32 v2, 0
	s_addc_u32 s11, s21, 0
	s_mov_b32 s20, 0
	s_add_i32 s39, s20, 2
	s_add_u32 s21, s10, 0xfffc0080
	s_addc_u32 s24, s11, -1
	s_add_i32 s40, 0, 0x10000
	s_cmp_eq_u32 s34, s20
	s_cselect_b32 s25, s7, s24
	s_cselect_b32 s24, s9, s21
	s_cselect_b32 s21, s35, s38
	s_cselect_b32 s20, s36, s37
	s_add_i32 s42, 0, 0x14000
	v_add_u32_e32 v142, s40, v187
	v_add_u32_e32 v158, s42, v187
	ds_read_b128 v[130:133], v142
	ds_read_b128 v[134:137], v142 offset:1024
	ds_read_b128 v[138:141], v142 offset:2048
	ds_read_b128 v[142:145], v142 offset:3072
	ds_read_b128 v[146:149], v158
	ds_read_b128 v[150:153], v158 offset:1024
	ds_read_b128 v[154:157], v158 offset:2048
	ds_read_b128 v[158:161], v158 offset:3072
	v_lshl_add_u64 v[184:185], s[10:11], 0, v[174:175]
	s_add_i32 m0, s13, 0xc000
	ds_read_b128 v[162:165], v204
	ds_read_b128 v[176:179], v204 offset:1024
	ds_read_b128 v[180:183], v204 offset:2048
	ds_read_b128 v[206:209], v204 offset:3072
	ds_read_b128 v[218:221], v204 offset:4096
	ds_read_b128 v[232:235], v204 offset:5120
	ds_read_b128 v[236:239], v204 offset:6144
	ds_read_b128 v[240:243], v204 offset:7168
	global_load_lds_dwordx4 v[184:185], off
	v_lshl_add_u64 v[184:185], s[10:11], 0, v[172:173]
	s_add_i32 m0, s13, 0xe000
	s_nop 0
	global_load_lds_dwordx4 v[184:185], off
	s_waitcnt vmcnt(8)
	s_waitcnt lgkmcnt(0)
	s_barrier
	s_setprio 1
	s_waitcnt lgkmcnt(0)
	v_mfma_f32_16x16x32_bf16 v[126:129], v[130:133], v[162:165], 0
	v_mfma_f32_16x16x32_bf16 v[122:125], v[138:141], v[162:165], 0
	v_mfma_f32_16x16x32_bf16 v[118:121], v[130:133], v[180:183], 0
	v_mfma_f32_16x16x32_bf16 v[114:117], v[138:141], v[180:183], 0
	v_mfma_f32_16x16x32_bf16 v[110:113], v[130:133], v[218:221], 0
	v_mfma_f32_16x16x32_bf16 v[106:109], v[138:141], v[218:221], 0
	v_mfma_f32_16x16x32_bf16 v[102:105], v[130:133], v[236:239], 0
	v_mfma_f32_16x16x32_bf16 v[98:101], v[138:141], v[236:239], 0
	v_mfma_f32_16x16x32_bf16 v[126:129], v[134:137], v[176:179], v[126:129]
	v_mfma_f32_16x16x32_bf16 v[122:125], v[142:145], v[176:179], v[122:125]
	v_mfma_f32_16x16x32_bf16 v[118:121], v[134:137], v[206:209], v[118:121]
	v_mfma_f32_16x16x32_bf16 v[114:117], v[142:145], v[206:209], v[114:117]
	v_mfma_f32_16x16x32_bf16 v[110:113], v[134:137], v[232:235], v[110:113]
	v_mfma_f32_16x16x32_bf16 v[106:109], v[142:145], v[232:235], v[106:109]
	v_mfma_f32_16x16x32_bf16 v[102:105], v[134:137], v[240:243], v[102:105]
	v_mfma_f32_16x16x32_bf16 v[98:101], v[142:145], v[240:243], v[98:101]
	s_setprio 0
	s_setprio 1
	v_mfma_f32_16x16x32_bf16 v[62:65], v[146:149], v[162:165], 0
	v_mfma_f32_16x16x32_bf16 v[58:61], v[154:157], v[162:165], 0
	v_mfma_f32_16x16x32_bf16 v[54:57], v[146:149], v[180:183], 0
	v_mfma_f32_16x16x32_bf16 v[50:53], v[154:157], v[180:183], 0
	v_mfma_f32_16x16x32_bf16 v[46:49], v[146:149], v[218:221], 0
	v_mfma_f32_16x16x32_bf16 v[42:45], v[154:157], v[218:221], 0
	v_mfma_f32_16x16x32_bf16 v[38:41], v[146:149], v[236:239], 0
	v_mfma_f32_16x16x32_bf16 v[34:37], v[154:157], v[236:239], 0
	v_mfma_f32_16x16x32_bf16 v[62:65], v[150:153], v[176:179], v[62:65]
	v_mfma_f32_16x16x32_bf16 v[58:61], v[158:161], v[176:179], v[58:61]
	v_mfma_f32_16x16x32_bf16 v[54:57], v[150:153], v[206:209], v[54:57]
	v_mfma_f32_16x16x32_bf16 v[50:53], v[158:161], v[206:209], v[50:53]
	v_mfma_f32_16x16x32_bf16 v[46:49], v[150:153], v[232:235], v[46:49]
	v_mfma_f32_16x16x32_bf16 v[42:45], v[158:161], v[232:235], v[42:45]
	v_mfma_f32_16x16x32_bf16 v[38:41], v[150:153], v[240:243], v[38:41]
	v_mfma_f32_16x16x32_bf16 v[34:37], v[158:161], v[240:243], v[34:37]
	s_setprio 0
	s_barrier
	s_add_i32 s40, s40, s12
	v_lshl_add_u64 v[184:185], s[20:21], 0, v[0:1]
	s_mov_b32 m0, s40
	ds_read_b128 v[162:165], v204 offset:16384
	ds_read_b128 v[176:179], v204 offset:17408
	ds_read_b128 v[180:183], v204 offset:18432
	ds_read_b128 v[206:209], v204 offset:19456
	ds_read_b128 v[218:221], v204 offset:20480
	ds_read_b128 v[232:235], v204 offset:21504
	ds_read_b128 v[236:239], v204 offset:22528
	ds_read_b128 v[240:243], v204 offset:23552
	global_load_lds_dwordx4 v[184:185], off
	s_add_i32 m0, s40, 0x2000
	s_add_u32 s40, s20, 0x40000
	v_lshl_add_u64 v[190:191], s[20:21], 0, v[170:171]
	s_addc_u32 s41, s21, 0
	s_add_i32 s42, s42, s12
	global_load_lds_dwordx4 v[190:191], off
	v_lshl_add_u64 v[192:193], s[40:41], 0, v[0:1]
	s_mov_b32 m0, s42
	v_lshl_add_u64 v[194:195], s[24:25], 0, v[168:169]
	global_load_lds_dwordx4 v[192:193], off
	v_lshl_add_u64 v[192:193], s[40:41], 0, v[170:171]
	s_add_i32 m0, s42, 0x2000
	s_nop 0
	global_load_lds_dwordx4 v[192:193], off
	v_lshl_add_u64 v[192:193], s[24:25], 0, v[166:167]
	s_mov_b32 m0, s13
	s_nop 0
	global_load_lds_dwordx4 v[192:193], off
	s_mov_b32 m0, s15
	s_nop 0
	global_load_lds_dwordx4 v[194:195], off
	s_waitcnt vmcnt(8)
	s_waitcnt lgkmcnt(0)
	s_barrier
; #define PG8_STAGE(bufoff, gbase, voff) do { _Pragma("unroll") for (int _i = 0; _i < 2; ++_i) \
;         __builtin_amdgcn_global_load_lds((const unsigned*)((const char*)(gbase) + (voff)[_i]), (LAS unsigned*)(lds + (bufoff) + ldsw + _i * 8192), 16, 0, 0); } while (0)
; #define PG8_LDA(dst, b, h) do { _Pragma("unroll") for (int m = 0; m < 4; ++m) _Pragma("unroll") for (int k = 0; k < 2; ++k) dst[m][k] = *(const LAS bf16x8*)(lds + PG8_SA(b, h) + aoff + m * 2048 + k * 1024); } while (0)
; #define PG8_LDB(dst, b, h) do { _Pragma("unroll") for (int n = 0; n < 2; ++n) _Pragma("unroll") for (int k = 0; k < 2; ++k) dst[n][k] = *(const LAS bf16x8*)(lds + PG8_SB(b, h) + boff + n * 2048 + k * 1024); } while (0)
; #define PG8_MMA(ai, bj, At, Bt) do { __builtin_amdgcn_s_setprio(1); _Pragma("unroll") for (int m = 0; m < 4; ++m) _Pragma("unroll") for (int n = 0; n < 2; ++n) _Pragma("unroll") for (int k = 0; k < 2; ++k) \
;         acc[ai][bj][m][n] = __builtin_amdgcn_mfma_f32_16x16x32_bf16(Bt[n][k], At[m][k], acc[ai][bj][m][n], 0, 0, 0); __builtin_amdgcn_s_setprio(0); } while (0)
; #define PG8_WAIT_V(n) asm volatile("s_waitcnt vmcnt(" #n ")" ::: "memory")
; #define PG8_WAIT_L(n) asm volatile("s_waitcnt lgkmcnt(" #n ")" ::: "memory")
; #define PG8_BAR __builtin_amdgcn_s_barrier()
; #define PG8_SCHED __builtin_amdgcn_sched_barrier(0)
; #define PG8_LDA(dst, b, h) do { _Pragma("unroll") for (int m = 0; m < 4; ++m) _Pragma("unroll") for (int k = 0; k < 2; ++k) dst[m][k] = *(const LAS bf16x8*)(lds + PG8_SA(b, h) + aoff + m * 2048 + k * 1024); } while (0)
; template <class Epi, class Sched>
; __device__ __forceinline__ void gemm_phase(LAS unsigned char* lds, const Gemm g, const Sched S, const Epi E, const int tid) {
;     ...
;             PG8_WAIT_V(8); PG8_WAIT_L(0); PG8_BAR; PG8_MMA(0, 0, At, B0); PG8_MMA(0, 1, At, B1); PG8_BAR; PG8_SCHED;
;             PG8_LDA(At, 0, 1); PG8_STAGE(PG8_SB(0, 0), b2, voffB); PG8_STAGE(PG8_SB(0, 1), b2 + hstepB, voffB); PG8_STAGE(PG8_SA(0, 0), a2, voffA);
;             PG8_WAIT_V(8); PG8_WAIT_L(0); PG8_BAR; PG8_MMA(1, 0, At, B0); PG8_MMA(1, 1, At, B1); PG8_BAR; PG8_SCHED;
;             PG8_LDB(B0, 1, 0); PG8_LDB(B1, 1, 1); PG8_SCHED; PG8_LDA(At, 1, 0); PG8_STAGE(PG8_SA(0, 1), a2 + hstepA, voffA);
;             PG8_WAIT_V(8); PG8_WAIT_L(0); PG8_BAR; PG8_MMA(0, 0, At, B0); PG8_MMA(0, 1, At, B1); PG8_BAR; PG8_SCHED;
	s_setprio 1
	s_waitcnt lgkmcnt(0)
	v_mfma_f32_16x16x32_bf16 v[94:97], v[130:133], v[162:165], 0
	v_mfma_f32_16x16x32_bf16 v[90:93], v[138:141], v[162:165], 0
	v_mfma_f32_16x16x32_bf16 v[86:89], v[130:133], v[180:183], 0
	v_mfma_f32_16x16x32_bf16 v[82:85], v[138:141], v[180:183], 0
	v_mfma_f32_16x16x32_bf16 v[78:81], v[130:133], v[218:221], 0
	v_mfma_f32_16x16x32_bf16 v[74:77], v[138:141], v[218:221], 0
	v_mfma_f32_16x16x32_bf16 v[70:73], v[130:133], v[236:239], 0
	v_mfma_f32_16x16x32_bf16 v[66:69], v[138:141], v[236:239], 0
	v_mfma_f32_16x16x32_bf16 v[94:97], v[134:137], v[176:179], v[94:97]
	v_mfma_f32_16x16x32_bf16 v[90:93], v[142:145], v[176:179], v[90:93]
	v_mfma_f32_16x16x32_bf16 v[86:89], v[134:137], v[206:209], v[86:89]
	v_mfma_f32_16x16x32_bf16 v[82:85], v[142:145], v[206:209], v[82:85]
	v_mfma_f32_16x16x32_bf16 v[78:81], v[134:137], v[232:235], v[78:81]
	v_mfma_f32_16x16x32_bf16 v[74:77], v[142:145], v[232:235], v[74:77]
	v_mfma_f32_16x16x32_bf16 v[70:73], v[134:137], v[240:243], v[70:73]
	v_mfma_f32_16x16x32_bf16 v[66:69], v[142:145], v[240:243], v[66:69]
	s_setprio 0
	s_setprio 1
	v_mfma_f32_16x16x32_bf16 v[30:33], v[146:149], v[162:165], 0
	v_mfma_f32_16x16x32_bf16 v[26:29], v[154:157], v[162:165], 0
	v_mfma_f32_16x16x32_bf16 v[22:25], v[146:149], v[180:183], 0
	v_mfma_f32_16x16x32_bf16 v[18:21], v[154:157], v[180:183], 0
	v_mfma_f32_16x16x32_bf16 v[14:17], v[146:149], v[218:221], 0
	v_mfma_f32_16x16x32_bf16 v[10:13], v[154:157], v[218:221], 0
	v_mfma_f32_16x16x32_bf16 v[6:9], v[146:149], v[236:239], 0
	v_mfma_f32_16x16x32_bf16 v[2:5], v[154:157], v[236:239], 0
	v_mfma_f32_16x16x32_bf16 v[30:33], v[150:153], v[176:179], v[30:33]
	v_mfma_f32_16x16x32_bf16 v[26:29], v[158:161], v[176:179], v[26:29]
	v_mfma_f32_16x16x32_bf16 v[22:25], v[150:153], v[206:209], v[22:25]
	v_mfma_f32_16x16x32_bf16 v[18:21], v[158:161], v[206:209], v[18:21]
	v_mfma_f32_16x16x32_bf16 v[14:17], v[150:153], v[232:235], v[14:17]
	v_mfma_f32_16x16x32_bf16 v[10:13], v[158:161], v[232:235], v[10:13]
	v_mfma_f32_16x16x32_bf16 v[6:9], v[150:153], v[240:243], v[6:9]
	v_mfma_f32_16x16x32_bf16 v[2:5], v[158:161], v[240:243], v[2:5]
	s_setprio 0
	s_barrier
	s_add_i32 s40, 0, 0x18000
	s_add_i32 s41, 0, 0x1c000
	v_add_u32_e32 v142, s40, v187
	v_add_u32_e32 v158, s41, v187
	ds_read_b128 v[130:133], v142
	ds_read_b128 v[134:137], v142 offset:1024
	ds_read_b128 v[138:141], v142 offset:2048
	ds_read_b128 v[142:145], v142 offset:3072
	ds_read_b128 v[146:149], v158
	ds_read_b128 v[150:153], v158 offset:1024
	ds_read_b128 v[154:157], v158 offset:2048
	ds_read_b128 v[158:161], v158 offset:3072
	s_add_u32 s24, s24, 0x40000
	s_addc_u32 s25, s25, 0
	s_mov_b32 m0, s18
	v_lshl_add_u64 v[210:211], s[24:25], 0, v[166:167]
	ds_read_b128 v[162:165], v204 offset:32768
	ds_read_b128 v[176:179], v204 offset:33792
	ds_read_b128 v[180:183], v204 offset:34816
	ds_read_b128 v[206:209], v204 offset:35840
	ds_read_b128 v[218:221], v204 offset:36864
	ds_read_b128 v[232:235], v204 offset:37888
	ds_read_b128 v[236:239], v204 offset:38912
	ds_read_b128 v[240:243], v204 offset:39936
	global_load_lds_dwordx4 v[210:211], off
	v_lshl_add_u64 v[210:211], s[24:25], 0, v[168:169]
	s_mov_b32 m0, s19
	s_nop 0
	global_load_lds_dwordx4 v[210:211], off
	s_waitcnt vmcnt(8)
	s_waitcnt lgkmcnt(0)
	s_barrier
	s_setprio 1
	s_waitcnt lgkmcnt(0)
	v_mfma_f32_16x16x32_bf16 v[126:129], v[130:133], v[162:165], v[126:129]
	v_mfma_f32_16x16x32_bf16 v[122:125], v[138:141], v[162:165], v[122:125]
	v_mfma_f32_16x16x32_bf16 v[118:121], v[130:133], v[180:183], v[118:121]
	v_mfma_f32_16x16x32_bf16 v[114:117], v[138:141], v[180:183], v[114:117]
	v_mfma_f32_16x16x32_bf16 v[110:113], v[130:133], v[218:221], v[110:113]
	v_mfma_f32_16x16x32_bf16 v[106:109], v[138:141], v[218:221], v[106:109]
	v_mfma_f32_16x16x32_bf16 v[102:105], v[130:133], v[236:239], v[102:105]
	v_mfma_f32_16x16x32_bf16 v[98:101], v[138:141], v[236:239], v[98:101]
	v_mfma_f32_16x16x32_bf16 v[126:129], v[134:137], v[176:179], v[126:129]
	v_mfma_f32_16x16x32_bf16 v[122:125], v[142:145], v[176:179], v[122:125]
	v_mfma_f32_16x16x32_bf16 v[118:121], v[134:137], v[206:209], v[118:121]
	v_mfma_f32_16x16x32_bf16 v[114:117], v[142:145], v[206:209], v[114:117]
	v_mfma_f32_16x16x32_bf16 v[110:113], v[134:137], v[232:235], v[110:113]
	v_mfma_f32_16x16x32_bf16 v[106:109], v[142:145], v[232:235], v[106:109]
	v_mfma_f32_16x16x32_bf16 v[102:105], v[134:137], v[240:243], v[102:105]
	v_mfma_f32_16x16x32_bf16 v[98:101], v[142:145], v[240:243], v[98:101]
	s_setprio 0
	s_setprio 1
	v_mfma_f32_16x16x32_bf16 v[62:65], v[146:149], v[162:165], v[62:65]
	v_mfma_f32_16x16x32_bf16 v[58:61], v[154:157], v[162:165], v[58:61]
	v_mfma_f32_16x16x32_bf16 v[54:57], v[146:149], v[180:183], v[54:57]
	v_mfma_f32_16x16x32_bf16 v[50:53], v[154:157], v[180:183], v[50:53]
	v_mfma_f32_16x16x32_bf16 v[46:49], v[146:149], v[218:221], v[46:49]
	v_mfma_f32_16x16x32_bf16 v[42:45], v[154:157], v[218:221], v[42:45]
	v_mfma_f32_16x16x32_bf16 v[38:41], v[146:149], v[236:239], v[38:41]
	v_mfma_f32_16x16x32_bf16 v[34:37], v[154:157], v[236:239], v[34:37]
	v_mfma_f32_16x16x32_bf16 v[62:65], v[150:153], v[176:179], v[62:65]
	v_mfma_f32_16x16x32_bf16 v[58:61], v[158:161], v[176:179], v[58:61]
	v_mfma_f32_16x16x32_bf16 v[54:57], v[150:153], v[206:209], v[54:57]
	v_mfma_f32_16x16x32_bf16 v[50:53], v[158:161], v[206:209], v[50:53]
	v_mfma_f32_16x16x32_bf16 v[46:49], v[150:153], v[232:235], v[46:49]
	v_mfma_f32_16x16x32_bf16 v[42:45], v[158:161], v[232:235], v[42:45]
	v_mfma_f32_16x16x32_bf16 v[38:41], v[150:153], v[240:243], v[38:41]
	v_mfma_f32_16x16x32_bf16 v[34:37], v[158:161], v[240:243], v[34:37]
	s_setprio 0
	s_barrier
; #define PG8_STAGE(bufoff, gbase, voff) do { _Pragma("unroll") for (int _i = 0; _i < 2; ++_i) \
;         __builtin_amdgcn_global_load_lds((const unsigned*)((const char*)(gbase) + (voff)[_i]), (LAS unsigned*)(lds + (bufoff) + ldsw + _i * 8192), 16, 0, 0); } while (0)
; #define PG8_LDA(dst, b, h) do { _Pragma("unroll") for (int m = 0; m < 4; ++m) _Pragma("unroll") for (int k = 0; k < 2; ++k) dst[m][k] = *(const LAS bf16x8*)(lds + PG8_SA(b, h) + aoff + m * 2048 + k * 1024); } while (0)
; #define PG8_MMA(ai, bj, At, Bt) do { __builtin_amdgcn_s_setprio(1); _Pragma("unroll") for (int m = 0; m < 4; ++m) _Pragma("unroll") for (int n = 0; n < 2; ++n) _Pragma("unroll") for (int k = 0; k < 2; ++k) \
;         acc[ai][bj][m][n] = __builtin_amdgcn_mfma_f32_16x16x32_bf16(Bt[n][k], At[m][k], acc[ai][bj][m][n], 0, 0, 0); __builtin_amdgcn_s_setprio(0); } while (0)
; #define PG8_WAIT_V(n) asm volatile("s_waitcnt vmcnt(" #n ")" ::: "memory")
; #define PG8_WAIT_L(n) asm volatile("s_waitcnt lgkmcnt(" #n ")" ::: "memory")
; #define PG8_BAR __builtin_amdgcn_s_barrier()
; #define PG8_SCHED __builtin_amdgcn_sched_barrier(0)
; #define PG8_STAGE(bufoff, gbase, voff, q64) do { \
;         __builtin_amdgcn_global_load_lds((const unsigned*)((const char*)(gbase) + (voff)), (LAS unsigned*)(lds + (bufoff) + ldsw), 16, 0, 0); \
;         __builtin_amdgcn_global_load_lds((const unsigned*)((const char*)(gbase) + (q64) + (voff)), (LAS unsigned*)(lds + (bufoff) + ldsw + 8192), 16, 0, 0); } while (0)
; #define PG8_LDA(dst, b, h) do { _Pragma("unroll") for (int m = 0; m < 4; ++m) _Pragma("unroll") for (int k = 0; k < 2; ++k) dst[m][k] = *(const LAS bf16x8*)(lds + PG8_SA(b, h) + aoff + m * 2048 + k * 1024); } while (0)
; #define PG8_WAIT_V(n) asm volatile("s_waitcnt vmcnt(" #n ")" ::: "memory")
; #define PG8_WAIT_L(n) asm volatile("s_waitcnt lgkmcnt(" #n ")" ::: "memory")
; #define PG8_BAR __builtin_amdgcn_s_barrier()
; template <class Epi, class Sched>
; __device__ __forceinline__ void gemm_phase(LAS unsigned char* lds, const Gemm g, const Sched S, const Epi E, const int tid) {
;     ...
;             PG8_LDA(At, 1, 1); PG8_STAGE(PG8_SB(1, 0), b3, voffB); PG8_STAGE(PG8_SB(1, 1), b3 + hstepB, voffB); PG8_STAGE(PG8_SA(1, 0), a3, voffA);
;             PG8_WAIT_V(8); PG8_WAIT_L(0); PG8_BAR; PG8_MMA(1, 0, At, B0); PG8_MMA(1, 1, At, B1); PG8_BAR; PG8_SCHED;
;         }
	s_add_i32 s24, s40, s12
	v_lshl_add_u64 v[184:185], v[184:185], 0, s[0:1]
	s_mov_b32 m0, s24
	ds_read_b128 v[162:165], v204 offset:49152
	ds_read_b128 v[176:179], v204 offset:50176
	ds_read_b128 v[180:183], v204 offset:51200
	ds_read_b128 v[206:209], v204 offset:52224
	ds_read_b128 v[218:221], v204 offset:53248
	ds_read_b128 v[232:235], v204 offset:54272
	ds_read_b128 v[236:239], v204 offset:55296
	ds_read_b128 v[240:243], v204 offset:56320
	global_load_lds_dwordx4 v[184:185], off
	s_add_i32 m0, s24, 0x2000
	s_add_u32 s20, s20, 0x40080
	v_lshl_add_u64 v[184:185], v[190:191], 0, s[0:1]
	s_addc_u32 s21, s21, 0
	s_add_i32 s24, s41, s12
	global_load_lds_dwordx4 v[184:185], off
	v_lshl_add_u64 v[184:185], s[20:21], 0, v[0:1]
	s_mov_b32 m0, s24
	s_nop 0
	global_load_lds_dwordx4 v[184:185], off
	v_lshl_add_u64 v[184:185], s[20:21], 0, v[170:171]
	s_add_i32 m0, s24, 0x2000
	s_nop 0
	global_load_lds_dwordx4 v[184:185], off
	v_lshl_add_u64 v[184:185], v[192:193], 0, s[0:1]
	s_mov_b32 m0, s29
	s_nop 0
	global_load_lds_dwordx4 v[184:185], off
	v_lshl_add_u64 v[184:185], v[194:195], 0, s[0:1]
	s_mov_b32 m0, s31
	s_nop 0
	global_load_lds_dwordx4 v[184:185], off
	s_waitcnt vmcnt(8)
	s_waitcnt lgkmcnt(0)
	s_barrier
	s_setprio 1
	s_waitcnt lgkmcnt(0)
	v_mfma_f32_16x16x32_bf16 v[94:97], v[130:133], v[162:165], v[94:97]
	v_mfma_f32_16x16x32_bf16 v[90:93], v[138:141], v[162:165], v[90:93]
	v_mfma_f32_16x16x32_bf16 v[86:89], v[130:133], v[180:183], v[86:89]
	v_mfma_f32_16x16x32_bf16 v[82:85], v[138:141], v[180:183], v[82:85]
	v_mfma_f32_16x16x32_bf16 v[78:81], v[130:133], v[218:221], v[78:81]
	v_mfma_f32_16x16x32_bf16 v[74:77], v[138:141], v[218:221], v[74:77]
	v_mfma_f32_16x16x32_bf16 v[70:73], v[130:133], v[236:239], v[70:73]
	v_mfma_f32_16x16x32_bf16 v[66:69], v[138:141], v[236:239], v[66:69]
	v_mfma_f32_16x16x32_bf16 v[94:97], v[134:137], v[176:179], v[94:97]
	v_mfma_f32_16x16x32_bf16 v[90:93], v[142:145], v[176:179], v[90:93]
	v_mfma_f32_16x16x32_bf16 v[86:89], v[134:137], v[206:209], v[86:89]
	v_mfma_f32_16x16x32_bf16 v[82:85], v[142:145], v[206:209], v[82:85]
	v_mfma_f32_16x16x32_bf16 v[78:81], v[134:137], v[232:235], v[78:81]
	v_mfma_f32_16x16x32_bf16 v[74:77], v[142:145], v[232:235], v[74:77]
	v_mfma_f32_16x16x32_bf16 v[70:73], v[134:137], v[240:243], v[70:73]
	v_mfma_f32_16x16x32_bf16 v[66:69], v[142:145], v[240:243], v[66:69]
	s_setprio 0
	s_setprio 1
	v_mfma_f32_16x16x32_bf16 v[30:33], v[146:149], v[162:165], v[30:33]
	v_mfma_f32_16x16x32_bf16 v[26:29], v[154:157], v[162:165], v[26:29]
	v_mfma_f32_16x16x32_bf16 v[22:25], v[146:149], v[180:183], v[22:25]
	v_mfma_f32_16x16x32_bf16 v[18:21], v[154:157], v[180:183], v[18:21]
	v_mfma_f32_16x16x32_bf16 v[14:17], v[146:149], v[218:221], v[14:17]
	v_mfma_f32_16x16x32_bf16 v[10:13], v[154:157], v[218:221], v[10:13]
	v_mfma_f32_16x16x32_bf16 v[6:9], v[146:149], v[236:239], v[6:9]
	v_mfma_f32_16x16x32_bf16 v[2:5], v[154:157], v[236:239], v[2:5]
	v_mfma_f32_16x16x32_bf16 v[30:33], v[150:153], v[176:179], v[30:33]
	v_mfma_f32_16x16x32_bf16 v[26:29], v[158:161], v[176:179], v[26:29]
	v_mfma_f32_16x16x32_bf16 v[22:25], v[150:153], v[206:209], v[22:25]
	v_mfma_f32_16x16x32_bf16 v[18:21], v[158:161], v[206:209], v[18:21]
	v_mfma_f32_16x16x32_bf16 v[14:17], v[150:153], v[232:235], v[14:17]
	v_mfma_f32_16x16x32_bf16 v[10:13], v[158:161], v[232:235], v[10:13]
	v_mfma_f32_16x16x32_bf16 v[6:9], v[150:153], v[240:243], v[6:9]
	v_mfma_f32_16x16x32_bf16 v[2:5], v[158:161], v[240:243], v[2:5]
	s_setprio 0
	s_barrier
	s_add_u32 s37, s37, 0x100
	s_addc_u32 s38, s38, 0
	s_add_u32 s10, s10, 0x100
	s_addc_u32 s11, s11, 0
	s_cmp_ge_i32 s39, s28
	s_mov_b32 s20, s39
	s_cbranch_scc1 .Lpl93_exit

; #define PG8_BAR __builtin_amdgcn_s_barrier()
; #define PG8_BAR __builtin_amdgcn_s_barrier()
; template <class Epi, class Sched>
; __device__ __forceinline__ void gemm_phase(LAS unsigned char* lds, const Gemm g, const Sched S, const Epi E, const int tid) {
;     ...
;         if (wr == 0) PG8_BAR;
;         E(acc, cur, wr, wc, fr, fq, rc);
.Lpl93_exit:
	v_readlane_b32 s36, v254, 54
	v_readlane_b32 s37, v254, 55
	v_readlane_b32 s38, v254, 56
	v_readlane_b32 s39, v254, 57

; template <class Epi, class Sched>
; __device__ __forceinline__ void gemm_phase(LAS unsigned char* lds, const Gemm g, const Sched S, const Epi E, const int tid) {
;     ...
;     f32x4 acc[2][2][4][2];
; #pragma unroll
;     for (int a = 0; a < 2; ++a)
; #pragma unroll
;         for (int b = 0; b < 2; ++b)
; #pragma unroll
;             for (int m = 0; m < 4; ++m)
; #pragma unroll
;                 for (int n = 0; n < 2; ++n) acc[a][b][m][n] = (f32x4){0.f, 0.f, 0.f, 0.f};
.Lpl93_zero:
	v_mov_b32_e32 v129, 0
	v_mov_b32_e32 v128, v129
	v_mov_b32_e32 v127, v129
	v_mov_b32_e32 v126, v129
	v_mov_b32_e32 v125, v129
	v_mov_b32_e32 v124, v129
	v_mov_b32_e32 v123, v129
	v_mov_b32_e32 v122, v129
	v_mov_b32_e32 v121, v129
	v_mov_b32_e32 v120, v129
	v_mov_b32_e32 v119, v129
	v_mov_b32_e32 v118, v129
	v_mov_b32_e32 v117, v129
	v_mov_b32_e32 v116, v129
	v_mov_b32_e32 v115, v129
	v_mov_b32_e32 v114, v129
	v_mov_b32_e32 v113, v129
	v_mov_b32_e32 v112, v129
	v_mov_b32_e32 v111, v129
	v_mov_b32_e32 v110, v129
	v_mov_b32_e32 v109, v129
	v_mov_b32_e32 v108, v129
	v_mov_b32_e32 v107, v129
	v_mov_b32_e32 v106, v129
	v_mov_b32_e32 v105, v129
	v_mov_b32_e32 v104, v129
	v_mov_b32_e32 v103, v129
	v_mov_b32_e32 v102, v129
	v_mov_b32_e32 v101, v129
	v_mov_b32_e32 v100, v129
	v_mov_b32_e32 v99, v129
	v_mov_b32_e32 v98, v129
	v_mov_b32_e32 v65, v129
	v_mov_b32_e32 v64, v129
	v_mov_b32_e32 v63, v129
	v_mov_b32_e32 v62, v129
	v_mov_b32_e32 v61, v129
	v_mov_b32_e32 v60, v129
	v_mov_b32_e32 v59, v129
	v_mov_b32_e32 v58, v129
	v_mov_b32_e32 v57, v129
	v_mov_b32_e32 v56, v129
	v_mov_b32_e32 v55, v129
	v_mov_b32_e32 v54, v129
	v_mov_b32_e32 v53, v129
	v_mov_b32_e32 v52, v129
	v_mov_b32_e32 v51, v129
	v_mov_b32_e32 v50, v129
	v_mov_b32_e32 v49, v129
	v_mov_b32_e32 v48, v129
	v_mov_b32_e32 v47, v129
	v_mov_b32_e32 v46, v129
	v_mov_b32_e32 v45, v129
	v_mov_b32_e32 v44, v129
	v_mov_b32_e32 v43, v129
	v_mov_b32_e32 v42, v129
	v_mov_b32_e32 v41, v129
	v_mov_b32_e32 v40, v129
	v_mov_b32_e32 v39, v129
	v_mov_b32_e32 v38, v129
	v_mov_b32_e32 v37, v129
	v_mov_b32_e32 v36, v129
	v_mov_b32_e32 v35, v129
	v_mov_b32_e32 v34, v129
	v_mov_b32_e32 v97, v129
	v_mov_b32_e32 v96, v129
	v_mov_b32_e32 v95, v129
	v_mov_b32_e32 v94, v129
	v_mov_b32_e32 v93, v129
	v_mov_b32_e32 v92, v129
	v_mov_b32_e32 v91, v129
	v_mov_b32_e32 v90, v129
	v_mov_b32_e32 v89, v129
	v_mov_b32_e32 v88, v129
	v_mov_b32_e32 v87, v129
	v_mov_b32_e32 v86, v129
	v_mov_b32_e32 v85, v129
	v_mov_b32_e32 v84, v129
	v_mov_b32_e32 v83, v129
	v_mov_b32_e32 v82, v129
	v_mov_b32_e32 v81, v129
	v_mov_b32_e32 v80, v129
	v_mov_b32_e32 v79, v129
	v_mov_b32_e32 v78, v129
	v_mov_b32_e32 v77, v129
	v_mov_b32_e32 v76, v129
	v_mov_b32_e32 v75, v129
	v_mov_b32_e32 v74, v129
	v_mov_b32_e32 v73, v129
	v_mov_b32_e32 v72, v129
	v_mov_b32_e32 v71, v129
	v_mov_b32_e32 v70, v129
	v_mov_b32_e32 v69, v129
	v_mov_b32_e32 v68, v129
	v_mov_b32_e32 v67, v129
	v_mov_b32_e32 v66, v129
	v_mov_b32_e32 v33, v129
	v_mov_b32_e32 v32, v129
	v_mov_b32_e32 v31, v129
	v_mov_b32_e32 v30, v129
	v_mov_b32_e32 v29, v129
	v_mov_b32_e32 v28, v129
	v_mov_b32_e32 v27, v129
	v_mov_b32_e32 v26, v129
	v_mov_b32_e32 v25, v129
	v_mov_b32_e32 v24, v129
	v_mov_b32_e32 v23, v129
	v_mov_b32_e32 v22, v129
	v_mov_b32_e32 v21, v129
	v_mov_b32_e32 v20, v129
	v_mov_b32_e32 v19, v129
	v_mov_b32_e32 v18, v129
	v_mov_b32_e32 v17, v129
	v_mov_b32_e32 v16, v129
	v_mov_b32_e32 v15, v129
	v_mov_b32_e32 v14, v129
	v_mov_b32_e32 v13, v129
	v_mov_b32_e32 v12, v129
	v_mov_b32_e32 v11, v129
	v_mov_b32_e32 v10, v129
	v_mov_b32_e32 v9, v129
	v_mov_b32_e32 v8, v129
	v_mov_b32_e32 v7, v129
	v_mov_b32_e32 v6, v129
	v_mov_b32_e32 v5, v129
	v_mov_b32_e32 v4, v129
	v_mov_b32_e32 v3, v129
	v_mov_b32_e32 v2, v129
	s_branch .LBB0_95

; template <class Epi, class Sched>
; __device__ __forceinline__ void gemm_phase(LAS unsigned char* lds, const Gemm g, const Sched S, const Epi E, const int tid) {
;     ...
;     f32x4 acc[2][2][4][2];
; #pragma unroll
;     for (int a = 0; a < 2; ++a)
; #pragma unroll
;         for (int b = 0; b < 2; ++b)
; #pragma unroll
;             for (int m = 0; m < 4; ++m)
; #pragma unroll
;                 for (int n = 0; n < 2; ++n) acc[a][b][m][n] = (f32x4){0.f, 0.f, 0.f, 0.f};
;     bf16x8 At[4][2], B0[2][2], B1[2][2];
;     const char* cA = (const char*)g.A + (size_t)cur.pm * tstepA; const char* cB = (const char*)g.Bt + (size_t)cur.pn * tstepB;
;     PG8_STAGE(PG8_SB(0, 0), cB, voffB); PG8_STAGE(PG8_SB(0, 1), cB + hstepB, voffB); PG8_STAGE(PG8_SA(0, 0), cA, voffA); PG8_STAGE(PG8_SA(0, 1), cA + hstepA, voffA);
;     if (wr == 1) PG8_BAR;
;     PG8_WAIT_V(2); PG8_BAR;
;     PG8_STAGE(PG8_SB(1, 0), cB + kstep, voffB); PG8_STAGE(PG8_SA(1, 0), cA + kstep, voffA); PG8_STAGE(PG8_SB(1, 1), cB + hstepB + kstep, voffB);
;     PG8_WAIT_V(6); PG8_BAR;
;     for (;;) {
;         const bool has_next = S.next(ui + 1, nxt);
;         const char* nA = has_next ? (const char*)g.A + (size_t)nxt.pm * tstepA : cA; const char* nB = has_next ? (const char*)g.Bt + (size_t)nxt.pn * tstepB : cB;
;         for (int t = 0; t < nt; t += 2) {
;             const bool last = (t == nt - 2);
;             const char* a1 = cA + (size_t)(t + 1) * kstep;
;             const char* a2 = last ? nA : cA + (size_t)(t + 2) * kstep; const char* b2 = last ? nB : cB + (size_t)(t + 2) * kstep;
;             const char* a3 = a2 + kstep; const char* b3 = b2 + kstep;
;             PG8_LDB(B0, 0, 0); PG8_LDB(B1, 0, 1); PG8_SCHED; PG8_LDA(At, 0, 0); PG8_STAGE(PG8_SA(1, 1), a1 + hstepA, voffA);
;             PG8_WAIT_V(8); PG8_WAIT_L(0); PG8_BAR; PG8_MMA(0, 0, At, B0); PG8_MMA(0, 1, At, B1); PG8_BAR; PG8_SCHED;
;             PG8_LDA(At, 0, 1); PG8_STAGE(PG8_SB(0, 0), b2, voffB); PG8_STAGE(PG8_SB(0, 1), b2 + hstepB, voffB); PG8_STAGE(PG8_SA(0, 0), a2, voffA);
;             PG8_WAIT_V(8); PG8_WAIT_L(0); PG8_BAR; PG8_MMA(1, 0, At, B0); PG8_MMA(1, 1, At, B1); PG8_BAR; PG8_SCHED;
;             PG8_LDB(B0, 1, 0); PG8_LDB(B1, 1, 1); PG8_SCHED; PG8_LDA(At, 1, 0); PG8_STAGE(PG8_SA(0, 1), a2 + hstepA, voffA);
;             PG8_WAIT_V(8); PG8_WAIT_L(0); PG8_BAR; PG8_MMA(0, 0, At, B0); PG8_MMA(0, 1, At, B1); PG8_BAR; PG8_SCHED;
.LBB0_141:
	s_ashr_i32 s23, s22, 31
	s_lshl_b64 s[26:27], s[22:23], 19
	v_readlane_b32 s28, v254, 44
	v_readlane_b32 s29, v254, 45
	s_add_u32 s26, s28, s26
	s_addc_u32 s27, s29, s27
	s_ashr_i32 s21, s20, 31
	s_lshl_b64 s[28:29], s[20:21], 19
	s_add_u32 s42, s13, s28
	s_addc_u32 s43, s14, s29
	s_andn2_b64 vcc, exec, s[10:11]
	s_cbranch_vccnz .Lpl143_zero
	s_and_b64 s[28:29], s[4:5], exec
	s_cselect_b32 s21, s27, s25
	s_cselect_b32 s23, s26, s24
	s_cselect_b32 s37, s43, s7
	s_cselect_b32 s38, s42, s6
	s_add_u32 s39, s6, 0x100
	s_addc_u32 s40, s7, 0
	s_add_u32 s6, s24, 0x40080
	v_mov_b32_e32 v2, 0
	s_addc_u32 s7, s25, 0
	s_mov_b32 s24, 0
	s_add_i32 s41, s24, 2
	s_add_u32 s25, s6, 0xfffc0080
	s_addc_u32 s28, s7, -1
	s_add_i32 s49, 0, 0x10000
	s_cmp_eq_u32 s46, s24
	s_cselect_b32 s29, s21, s28
	s_cselect_b32 s28, s23, s25
	v_add_u32_e32 v144, s49, v146
	s_cselect_b32 s25, s37, s40
	s_cselect_b32 s24, s38, s39
	s_add_i32 s52, 0, 0x14000
	ds_read_b128 v[140:143], v144
	ds_read_b128 v[150:153], v144 offset:1024
	ds_read_b128 v[154:157], v144 offset:2048
	ds_read_b128 v[158:161], v144 offset:3072
	v_add_u32_e32 v144, s52, v146
	ds_read_b128 v[162:165], v144
	ds_read_b128 v[166:169], v144 offset:1024
	ds_read_b128 v[170:173], v144 offset:2048
	ds_read_b128 v[174:177], v144 offset:3072
	v_lshl_add_u64 v[190:191], s[6:7], 0, v[138:139]
	s_add_i32 m0, s18, 0xc000
	ds_read_b128 v[178:181], v149
	ds_read_b128 v[182:185], v149 offset:1024
	ds_read_b128 v[186:189], v149 offset:2048
	ds_read_b128 v[206:209], v149 offset:3072
	ds_read_b128 v[232:235], v149 offset:4096
	ds_read_b128 v[236:239], v149 offset:5120
	ds_read_b128 v[240:243], v149 offset:6144
	ds_read_b128 v[244:247], v149 offset:7168
	global_load_lds_dwordx4 v[190:191], off
	v_lshl_add_u64 v[190:191], s[6:7], 0, v[136:137]
	s_add_i32 m0, s18, 0xe000
	s_nop 0
	global_load_lds_dwordx4 v[190:191], off
	s_waitcnt vmcnt(8)
	s_waitcnt lgkmcnt(0)
	s_barrier
	s_setprio 1
	s_waitcnt lgkmcnt(0)
	v_mfma_f32_16x16x32_bf16 v[126:129], v[140:143], v[178:181], 0
	v_mfma_f32_16x16x32_bf16 v[122:125], v[154:157], v[178:181], 0
	v_mfma_f32_16x16x32_bf16 v[110:113], v[140:143], v[186:189], 0
	v_mfma_f32_16x16x32_bf16 v[106:109], v[154:157], v[186:189], 0
	v_mfma_f32_16x16x32_bf16 v[94:97], v[140:143], v[232:235], 0
	v_mfma_f32_16x16x32_bf16 v[90:93], v[154:157], v[232:235], 0
	v_mfma_f32_16x16x32_bf16 v[78:81], v[140:143], v[240:243], 0
	v_mfma_f32_16x16x32_bf16 v[74:77], v[154:157], v[240:243], 0
	v_mfma_f32_16x16x32_bf16 v[126:129], v[150:153], v[182:185], v[126:129]
	v_mfma_f32_16x16x32_bf16 v[122:125], v[158:161], v[182:185], v[122:125]
	v_mfma_f32_16x16x32_bf16 v[110:113], v[150:153], v[206:209], v[110:113]
	v_mfma_f32_16x16x32_bf16 v[106:109], v[158:161], v[206:209], v[106:109]
	v_mfma_f32_16x16x32_bf16 v[94:97], v[150:153], v[236:239], v[94:97]
	v_mfma_f32_16x16x32_bf16 v[90:93], v[158:161], v[236:239], v[90:93]
	v_mfma_f32_16x16x32_bf16 v[78:81], v[150:153], v[244:247], v[78:81]
	v_mfma_f32_16x16x32_bf16 v[74:77], v[158:161], v[244:247], v[74:77]
	s_setprio 0
	s_setprio 1
	v_mfma_f32_16x16x32_bf16 v[118:121], v[162:165], v[178:181], 0
	v_mfma_f32_16x16x32_bf16 v[114:117], v[170:173], v[178:181], 0
	v_mfma_f32_16x16x32_bf16 v[102:105], v[162:165], v[186:189], 0
	v_mfma_f32_16x16x32_bf16 v[98:101], v[170:173], v[186:189], 0
	v_mfma_f32_16x16x32_bf16 v[86:89], v[162:165], v[232:235], 0
	v_mfma_f32_16x16x32_bf16 v[82:85], v[170:173], v[232:235], 0
	v_mfma_f32_16x16x32_bf16 v[70:73], v[162:165], v[240:243], 0
	v_mfma_f32_16x16x32_bf16 v[66:69], v[170:173], v[240:243], 0
	v_mfma_f32_16x16x32_bf16 v[118:121], v[166:169], v[182:185], v[118:121]
	v_mfma_f32_16x16x32_bf16 v[114:117], v[174:177], v[182:185], v[114:117]
	v_mfma_f32_16x16x32_bf16 v[102:105], v[166:169], v[206:209], v[102:105]
	v_mfma_f32_16x16x32_bf16 v[98:101], v[174:177], v[206:209], v[98:101]
	v_mfma_f32_16x16x32_bf16 v[86:89], v[166:169], v[236:239], v[86:89]
	v_mfma_f32_16x16x32_bf16 v[82:85], v[174:177], v[236:239], v[82:85]
	v_mfma_f32_16x16x32_bf16 v[70:73], v[166:169], v[244:247], v[70:73]
	v_mfma_f32_16x16x32_bf16 v[66:69], v[174:177], v[244:247], v[66:69]
	s_setprio 0
	s_barrier
	s_add_i32 s49, s49, s15
	v_lshl_add_u64 v[190:191], s[24:25], 0, v[0:1]
	s_mov_b32 m0, s49
	ds_read_b128 v[178:181], v149 offset:16384
	ds_read_b128 v[182:185], v149 offset:17408
	ds_read_b128 v[186:189], v149 offset:18432
	ds_read_b128 v[206:209], v149 offset:19456
	ds_read_b128 v[232:235], v149 offset:20480
	ds_read_b128 v[236:239], v149 offset:21504
	ds_read_b128 v[240:243], v149 offset:22528
	ds_read_b128 v[244:247], v149 offset:23552
	global_load_lds_dwordx4 v[190:191], off
	s_add_i32 m0, s49, 0x2000
	s_add_u32 s50, s24, 0x40000
	v_lshl_add_u64 v[210:211], s[24:25], 0, v[134:135]
	s_addc_u32 s51, s25, 0
	s_add_i32 s49, s52, s15
	global_load_lds_dwordx4 v[210:211], off
	v_lshl_add_u64 v[218:219], s[50:51], 0, v[0:1]
	s_mov_b32 m0, s49
	v_lshl_add_u64 v[220:221], s[28:29], 0, v[132:133]
	global_load_lds_dwordx4 v[218:219], off
	v_lshl_add_u64 v[218:219], s[50:51], 0, v[134:135]
	s_add_i32 m0, s49, 0x2000
	s_nop 0
	global_load_lds_dwordx4 v[218:219], off
	v_lshl_add_u64 v[218:219], s[28:29], 0, v[130:131]
	s_mov_b32 m0, s18
	s_nop 0
	global_load_lds_dwordx4 v[218:219], off
	s_mov_b32 m0, s19
	s_nop 0
	global_load_lds_dwordx4 v[220:221], off
	s_waitcnt vmcnt(8)
	s_waitcnt lgkmcnt(0)
	s_barrier
; #define PG8_STAGE(bufoff, gbase, voff) do { _Pragma("unroll") for (int _i = 0; _i < 2; ++_i) \
;         __builtin_amdgcn_global_load_lds((const unsigned*)((const char*)(gbase) + (voff)[_i]), (LAS unsigned*)(lds + (bufoff) + ldsw + _i * 8192), 16, 0, 0); } while (0)
; #define PG8_LDA(dst, b, h) do { _Pragma("unroll") for (int m = 0; m < 4; ++m) _Pragma("unroll") for (int k = 0; k < 2; ++k) dst[m][k] = *(const LAS bf16x8*)(lds + PG8_SA(b, h) + aoff + m * 2048 + k * 1024); } while (0)
; #define PG8_LDB(dst, b, h) do { _Pragma("unroll") for (int n = 0; n < 2; ++n) _Pragma("unroll") for (int k = 0; k < 2; ++k) dst[n][k] = *(const LAS bf16x8*)(lds + PG8_SB(b, h) + boff + n * 2048 + k * 1024); } while (0)
; #define PG8_MMA(ai, bj, At, Bt) do { __builtin_amdgcn_s_setprio(1); _Pragma("unroll") for (int m = 0; m < 4; ++m) _Pragma("unroll") for (int n = 0; n < 2; ++n) _Pragma("unroll") for (int k = 0; k < 2; ++k) \
;         acc[ai][bj][m][n] = __builtin_amdgcn_mfma_f32_16x16x32_bf16(Bt[n][k], At[m][k], acc[ai][bj][m][n], 0, 0, 0); __builtin_amdgcn_s_setprio(0); } while (0)
; #define PG8_WAIT_V(n) asm volatile("s_waitcnt vmcnt(" #n ")" ::: "memory")
; #define PG8_WAIT_L(n) asm volatile("s_waitcnt lgkmcnt(" #n ")" ::: "memory")
; #define PG8_BAR __builtin_amdgcn_s_barrier()
; #define PG8_SCHED __builtin_amdgcn_sched_barrier(0)
; #define PG8_LDA(dst, b, h) do { _Pragma("unroll") for (int m = 0; m < 4; ++m) _Pragma("unroll") for (int k = 0; k < 2; ++k) dst[m][k] = *(const LAS bf16x8*)(lds + PG8_SA(b, h) + aoff + m * 2048 + k * 1024); } while (0)
; template <class Epi, class Sched>
; __device__ __forceinline__ void gemm_phase(LAS unsigned char* lds, const Gemm g, const Sched S, const Epi E, const int tid) {
;     ...
;             PG8_WAIT_V(8); PG8_WAIT_L(0); PG8_BAR; PG8_MMA(0, 0, At, B0); PG8_MMA(0, 1, At, B1); PG8_BAR; PG8_SCHED;
;             PG8_LDA(At, 0, 1); PG8_STAGE(PG8_SB(0, 0), b2, voffB); PG8_STAGE(PG8_SB(0, 1), b2 + hstepB, voffB); PG8_STAGE(PG8_SA(0, 0), a2, voffA);
;             PG8_WAIT_V(8); PG8_WAIT_L(0); PG8_BAR; PG8_MMA(1, 0, At, B0); PG8_MMA(1, 1, At, B1); PG8_BAR; PG8_SCHED;
;             PG8_LDB(B0, 1, 0); PG8_LDB(B1, 1, 1); PG8_SCHED; PG8_LDA(At, 1, 0); PG8_STAGE(PG8_SA(0, 1), a2 + hstepA, voffA);
;             PG8_WAIT_V(8); PG8_WAIT_L(0); PG8_BAR; PG8_MMA(0, 0, At, B0); PG8_MMA(0, 1, At, B1); PG8_BAR; PG8_SCHED;
	s_setprio 1
	s_waitcnt lgkmcnt(0)
	v_mfma_f32_16x16x32_bf16 v[62:65], v[140:143], v[178:181], 0
	v_mfma_f32_16x16x32_bf16 v[58:61], v[154:157], v[178:181], 0
	v_mfma_f32_16x16x32_bf16 v[46:49], v[140:143], v[186:189], 0
	v_mfma_f32_16x16x32_bf16 v[42:45], v[154:157], v[186:189], 0
	v_mfma_f32_16x16x32_bf16 v[30:33], v[140:143], v[232:235], 0
	v_mfma_f32_16x16x32_bf16 v[26:29], v[154:157], v[232:235], 0
	v_mfma_f32_16x16x32_bf16 v[14:17], v[140:143], v[240:243], 0
	v_mfma_f32_16x16x32_bf16 v[10:13], v[154:157], v[240:243], 0
	v_mfma_f32_16x16x32_bf16 v[62:65], v[150:153], v[182:185], v[62:65]
	v_mfma_f32_16x16x32_bf16 v[58:61], v[158:161], v[182:185], v[58:61]
	v_mfma_f32_16x16x32_bf16 v[46:49], v[150:153], v[206:209], v[46:49]
	v_mfma_f32_16x16x32_bf16 v[42:45], v[158:161], v[206:209], v[42:45]
	v_mfma_f32_16x16x32_bf16 v[30:33], v[150:153], v[236:239], v[30:33]
	v_mfma_f32_16x16x32_bf16 v[26:29], v[158:161], v[236:239], v[26:29]
	v_mfma_f32_16x16x32_bf16 v[14:17], v[150:153], v[244:247], v[14:17]
	v_mfma_f32_16x16x32_bf16 v[10:13], v[158:161], v[244:247], v[10:13]
	s_setprio 0
	s_setprio 1
	v_mfma_f32_16x16x32_bf16 v[54:57], v[162:165], v[178:181], 0
	v_mfma_f32_16x16x32_bf16 v[50:53], v[170:173], v[178:181], 0
	v_mfma_f32_16x16x32_bf16 v[38:41], v[162:165], v[186:189], 0
	v_mfma_f32_16x16x32_bf16 v[34:37], v[170:173], v[186:189], 0
	v_mfma_f32_16x16x32_bf16 v[22:25], v[162:165], v[232:235], 0
	v_mfma_f32_16x16x32_bf16 v[18:21], v[170:173], v[232:235], 0
	v_mfma_f32_16x16x32_bf16 v[6:9], v[162:165], v[240:243], 0
	v_mfma_f32_16x16x32_bf16 v[2:5], v[170:173], v[240:243], 0
	v_mfma_f32_16x16x32_bf16 v[54:57], v[166:169], v[182:185], v[54:57]
	v_mfma_f32_16x16x32_bf16 v[50:53], v[174:177], v[182:185], v[50:53]
	v_mfma_f32_16x16x32_bf16 v[38:41], v[166:169], v[206:209], v[38:41]
	v_mfma_f32_16x16x32_bf16 v[34:37], v[174:177], v[206:209], v[34:37]
	v_mfma_f32_16x16x32_bf16 v[22:25], v[166:169], v[236:239], v[22:25]
	v_mfma_f32_16x16x32_bf16 v[18:21], v[174:177], v[236:239], v[18:21]
	v_mfma_f32_16x16x32_bf16 v[6:9], v[166:169], v[244:247], v[6:9]
	v_mfma_f32_16x16x32_bf16 v[2:5], v[174:177], v[244:247], v[2:5]
	s_setprio 0
	s_barrier
	s_add_i32 s49, 0, 0x18000
	v_add_u32_e32 v144, s49, v146
	s_add_i32 s50, 0, 0x1c000
	ds_read_b128 v[140:143], v144
	ds_read_b128 v[150:153], v144 offset:1024
	ds_read_b128 v[154:157], v144 offset:2048
	ds_read_b128 v[158:161], v144 offset:3072
	v_add_u32_e32 v144, s50, v146
	ds_read_b128 v[162:165], v144
	ds_read_b128 v[166:169], v144 offset:1024
	ds_read_b128 v[170:173], v144 offset:2048
	ds_read_b128 v[174:177], v144 offset:3072
	s_add_u32 s28, s28, 0x40000
	s_addc_u32 s29, s29, 0
	s_mov_b32 m0, s31
	v_lshl_add_u64 v[248:249], s[28:29], 0, v[130:131]
	ds_read_b128 v[178:181], v149 offset:32768
	ds_read_b128 v[182:185], v149 offset:33792
	ds_read_b128 v[186:189], v149 offset:34816
	ds_read_b128 v[206:209], v149 offset:35840
	ds_read_b128 v[232:235], v149 offset:36864
	ds_read_b128 v[236:239], v149 offset:37888
	ds_read_b128 v[240:243], v149 offset:38912
	ds_read_b128 v[244:247], v149 offset:39936
	global_load_lds_dwordx4 v[248:249], off
	v_lshl_add_u64 v[248:249], s[28:29], 0, v[132:133]
	s_mov_b32 m0, s34
	s_nop 0
	global_load_lds_dwordx4 v[248:249], off
	s_waitcnt vmcnt(8)
	s_waitcnt lgkmcnt(0)
	s_barrier
	s_setprio 1
	s_waitcnt lgkmcnt(0)
	v_mfma_f32_16x16x32_bf16 v[126:129], v[140:143], v[178:181], v[126:129]
	v_mfma_f32_16x16x32_bf16 v[122:125], v[154:157], v[178:181], v[122:125]
	v_mfma_f32_16x16x32_bf16 v[110:113], v[140:143], v[186:189], v[110:113]
	v_mfma_f32_16x16x32_bf16 v[106:109], v[154:157], v[186:189], v[106:109]
	v_mfma_f32_16x16x32_bf16 v[94:97], v[140:143], v[232:235], v[94:97]
	v_mfma_f32_16x16x32_bf16 v[90:93], v[154:157], v[232:235], v[90:93]
	v_mfma_f32_16x16x32_bf16 v[78:81], v[140:143], v[240:243], v[78:81]
	v_mfma_f32_16x16x32_bf16 v[74:77], v[154:157], v[240:243], v[74:77]
	v_mfma_f32_16x16x32_bf16 v[126:129], v[150:153], v[182:185], v[126:129]
	v_mfma_f32_16x16x32_bf16 v[122:125], v[158:161], v[182:185], v[122:125]
	v_mfma_f32_16x16x32_bf16 v[110:113], v[150:153], v[206:209], v[110:113]
	v_mfma_f32_16x16x32_bf16 v[106:109], v[158:161], v[206:209], v[106:109]
	v_mfma_f32_16x16x32_bf16 v[94:97], v[150:153], v[236:239], v[94:97]
	v_mfma_f32_16x16x32_bf16 v[90:93], v[158:161], v[236:239], v[90:93]
	v_mfma_f32_16x16x32_bf16 v[78:81], v[150:153], v[244:247], v[78:81]
	v_mfma_f32_16x16x32_bf16 v[74:77], v[158:161], v[244:247], v[74:77]
	s_setprio 0
	s_setprio 1
	v_mfma_f32_16x16x32_bf16 v[118:121], v[162:165], v[178:181], v[118:121]
	v_mfma_f32_16x16x32_bf16 v[114:117], v[170:173], v[178:181], v[114:117]
	v_mfma_f32_16x16x32_bf16 v[102:105], v[162:165], v[186:189], v[102:105]
	v_mfma_f32_16x16x32_bf16 v[98:101], v[170:173], v[186:189], v[98:101]
	v_mfma_f32_16x16x32_bf16 v[86:89], v[162:165], v[232:235], v[86:89]
	v_mfma_f32_16x16x32_bf16 v[82:85], v[170:173], v[232:235], v[82:85]
	v_mfma_f32_16x16x32_bf16 v[70:73], v[162:165], v[240:243], v[70:73]
	v_mfma_f32_16x16x32_bf16 v[66:69], v[170:173], v[240:243], v[66:69]
	v_mfma_f32_16x16x32_bf16 v[118:121], v[166:169], v[182:185], v[118:121]
	v_mfma_f32_16x16x32_bf16 v[114:117], v[174:177], v[182:185], v[114:117]
	v_mfma_f32_16x16x32_bf16 v[102:105], v[166:169], v[206:209], v[102:105]
	v_mfma_f32_16x16x32_bf16 v[98:101], v[174:177], v[206:209], v[98:101]
	v_mfma_f32_16x16x32_bf16 v[86:89], v[166:169], v[236:239], v[86:89]
	v_mfma_f32_16x16x32_bf16 v[82:85], v[174:177], v[236:239], v[82:85]
	v_mfma_f32_16x16x32_bf16 v[70:73], v[166:169], v[244:247], v[70:73]
	v_mfma_f32_16x16x32_bf16 v[66:69], v[174:177], v[244:247], v[66:69]
	s_setprio 0
	s_barrier
; #define PG8_STAGE(bufoff, gbase, voff) do { _Pragma("unroll") for (int _i = 0; _i < 2; ++_i) \
;         __builtin_amdgcn_global_load_lds((const unsigned*)((const char*)(gbase) + (voff)[_i]), (LAS unsigned*)(lds + (bufoff) + ldsw + _i * 8192), 16, 0, 0); } while (0)
; #define PG8_LDA(dst, b, h) do { _Pragma("unroll") for (int m = 0; m < 4; ++m) _Pragma("unroll") for (int k = 0; k < 2; ++k) dst[m][k] = *(const LAS bf16x8*)(lds + PG8_SA(b, h) + aoff + m * 2048 + k * 1024); } while (0)
; #define PG8_MMA(ai, bj, At, Bt) do { __builtin_amdgcn_s_setprio(1); _Pragma("unroll") for (int m = 0; m < 4; ++m) _Pragma("unroll") for (int n = 0; n < 2; ++n) _Pragma("unroll") for (int k = 0; k < 2; ++k) \
;         acc[ai][bj][m][n] = __builtin_amdgcn_mfma_f32_16x16x32_bf16(Bt[n][k], At[m][k], acc[ai][bj][m][n], 0, 0, 0); __builtin_amdgcn_s_setprio(0); } while (0)
; #define PG8_WAIT_V(n) asm volatile("s_waitcnt vmcnt(" #n ")" ::: "memory")
; #define PG8_WAIT_L(n) asm volatile("s_waitcnt lgkmcnt(" #n ")" ::: "memory")
; #define PG8_BAR __builtin_amdgcn_s_barrier()
; #define PG8_SCHED __builtin_amdgcn_sched_barrier(0)
; #define PG8_STAGE(bufoff, gbase, voff, q64) do { \
;         __builtin_amdgcn_global_load_lds((const unsigned*)((const char*)(gbase) + (voff)), (LAS unsigned*)(lds + (bufoff) + ldsw), 16, 0, 0); \
;         __builtin_amdgcn_global_load_lds((const unsigned*)((const char*)(gbase) + (q64) + (voff)), (LAS unsigned*)(lds + (bufoff) + ldsw + 8192), 16, 0, 0); } while (0)
; #define PG8_LDA(dst, b, h) do { _Pragma("unroll") for (int m = 0; m < 4; ++m) _Pragma("unroll") for (int k = 0; k < 2; ++k) dst[m][k] = *(const LAS bf16x8*)(lds + PG8_SA(b, h) + aoff + m * 2048 + k * 1024); } while (0)
; #define PG8_WAIT_V(n) asm volatile("s_waitcnt vmcnt(" #n ")" ::: "memory")
; #define PG8_WAIT_L(n) asm volatile("s_waitcnt lgkmcnt(" #n ")" ::: "memory")
; #define PG8_BAR __builtin_amdgcn_s_barrier()
; template <class Epi, class Sched>
; __device__ __forceinline__ void gemm_phase(LAS unsigned char* lds, const Gemm g, const Sched S, const Epi E, const int tid) {
;     ...
;             PG8_LDA(At, 1, 1); PG8_STAGE(PG8_SB(1, 0), b3, voffB); PG8_STAGE(PG8_SB(1, 1), b3 + hstepB, voffB); PG8_STAGE(PG8_SA(1, 0), a3, voffA);
;             PG8_WAIT_V(8); PG8_WAIT_L(0); PG8_BAR; PG8_MMA(1, 0, At, B0); PG8_MMA(1, 1, At, B1); PG8_BAR; PG8_SCHED;
;         }
	s_add_i32 s28, s49, s15
	v_lshl_add_u64 v[190:191], v[190:191], 0, s[0:1]
	s_mov_b32 m0, s28
	ds_read_b128 v[178:181], v149 offset:49152
	ds_read_b128 v[182:185], v149 offset:50176
	ds_read_b128 v[186:189], v149 offset:51200
	ds_read_b128 v[206:209], v149 offset:52224
	ds_read_b128 v[232:235], v149 offset:53248
	ds_read_b128 v[236:239], v149 offset:54272
	ds_read_b128 v[240:243], v149 offset:55296
	ds_read_b128 v[244:247], v149 offset:56320
	global_load_lds_dwordx4 v[190:191], off
	s_add_i32 m0, s28, 0x2000
	s_add_u32 s24, s24, 0x40080
	v_lshl_add_u64 v[190:191], v[210:211], 0, s[0:1]
	s_addc_u32 s25, s25, 0
	s_add_i32 s28, s50, s15
	global_load_lds_dwordx4 v[190:191], off
	v_lshl_add_u64 v[190:191], s[24:25], 0, v[0:1]
	s_mov_b32 m0, s28
	s_nop 0
	global_load_lds_dwordx4 v[190:191], off
	v_lshl_add_u64 v[190:191], s[24:25], 0, v[134:135]
	s_add_i32 m0, s28, 0x2000
	s_nop 0
	global_load_lds_dwordx4 v[190:191], off
	v_lshl_add_u64 v[190:191], v[218:219], 0, s[0:1]
	s_mov_b32 m0, s44
	s_nop 0
	global_load_lds_dwordx4 v[190:191], off
	v_lshl_add_u64 v[190:191], v[220:221], 0, s[0:1]
	s_mov_b32 m0, s45
	s_nop 0
	global_load_lds_dwordx4 v[190:191], off
	s_waitcnt vmcnt(8)
	s_waitcnt lgkmcnt(0)
	s_barrier
	s_setprio 1
	s_waitcnt lgkmcnt(0)
	v_mfma_f32_16x16x32_bf16 v[62:65], v[140:143], v[178:181], v[62:65]
	v_mfma_f32_16x16x32_bf16 v[58:61], v[154:157], v[178:181], v[58:61]
	v_mfma_f32_16x16x32_bf16 v[46:49], v[140:143], v[186:189], v[46:49]
	v_mfma_f32_16x16x32_bf16 v[42:45], v[154:157], v[186:189], v[42:45]
	v_mfma_f32_16x16x32_bf16 v[30:33], v[140:143], v[232:235], v[30:33]
	v_mfma_f32_16x16x32_bf16 v[26:29], v[154:157], v[232:235], v[26:29]
	v_mfma_f32_16x16x32_bf16 v[14:17], v[140:143], v[240:243], v[14:17]
	v_mfma_f32_16x16x32_bf16 v[10:13], v[154:157], v[240:243], v[10:13]
	v_mfma_f32_16x16x32_bf16 v[62:65], v[150:153], v[182:185], v[62:65]
	v_mfma_f32_16x16x32_bf16 v[58:61], v[158:161], v[182:185], v[58:61]
	v_mfma_f32_16x16x32_bf16 v[46:49], v[150:153], v[206:209], v[46:49]
	v_mfma_f32_16x16x32_bf16 v[42:45], v[158:161], v[206:209], v[42:45]
	v_mfma_f32_16x16x32_bf16 v[30:33], v[150:153], v[236:239], v[30:33]
	v_mfma_f32_16x16x32_bf16 v[26:29], v[158:161], v[236:239], v[26:29]
	v_mfma_f32_16x16x32_bf16 v[14:17], v[150:153], v[244:247], v[14:17]
	v_mfma_f32_16x16x32_bf16 v[10:13], v[158:161], v[244:247], v[10:13]
	s_setprio 0
	s_setprio 1
	v_mfma_f32_16x16x32_bf16 v[54:57], v[162:165], v[178:181], v[54:57]
	v_mfma_f32_16x16x32_bf16 v[50:53], v[170:173], v[178:181], v[50:53]
	v_mfma_f32_16x16x32_bf16 v[38:41], v[162:165], v[186:189], v[38:41]
	v_mfma_f32_16x16x32_bf16 v[34:37], v[170:173], v[186:189], v[34:37]
	v_mfma_f32_16x16x32_bf16 v[22:25], v[162:165], v[232:235], v[22:25]
	v_mfma_f32_16x16x32_bf16 v[18:21], v[170:173], v[232:235], v[18:21]
	v_mfma_f32_16x16x32_bf16 v[6:9], v[162:165], v[240:243], v[6:9]
	v_mfma_f32_16x16x32_bf16 v[2:5], v[170:173], v[240:243], v[2:5]
	v_mfma_f32_16x16x32_bf16 v[54:57], v[166:169], v[182:185], v[54:57]
	v_mfma_f32_16x16x32_bf16 v[50:53], v[174:177], v[182:185], v[50:53]
	v_mfma_f32_16x16x32_bf16 v[38:41], v[166:169], v[206:209], v[38:41]
	v_mfma_f32_16x16x32_bf16 v[34:37], v[174:177], v[206:209], v[34:37]
	v_mfma_f32_16x16x32_bf16 v[22:25], v[166:169], v[236:239], v[22:25]
	v_mfma_f32_16x16x32_bf16 v[18:21], v[174:177], v[236:239], v[18:21]
	v_mfma_f32_16x16x32_bf16 v[6:9], v[166:169], v[244:247], v[6:9]
	v_mfma_f32_16x16x32_bf16 v[2:5], v[174:177], v[244:247], v[2:5]
	s_setprio 0
	s_barrier
	s_add_u32 s39, s39, 0x100
	s_addc_u32 s40, s40, 0
	s_add_u32 s6, s6, 0x100
	s_addc_u32 s7, s7, 0
	s_cmp_ge_i32 s41, s35
	s_mov_b32 s24, s41
	s_cbranch_scc1 .Lpl143_exit

; #define PG8_BAR __builtin_amdgcn_s_barrier()
; #define PG8_BAR __builtin_amdgcn_s_barrier()
; template <class Epi, class Sched>
; __device__ __forceinline__ void gemm_phase(LAS unsigned char* lds, const Gemm g, const Sched S, const Epi E, const int tid) {
;     ...
;         if (wr == 0) PG8_BAR;
;         E(acc, cur, wr, wc, fr, fq, rc);
.Lpl143_exit:
	v_readlane_b32 s38, v254, 48
	v_readlane_b32 s39, v254, 49

; template <class Epi, class Sched>
; __device__ __forceinline__ void gemm_phase(LAS unsigned char* lds, const Gemm g, const Sched S, const Epi E, const int tid) {
;     ...
;     f32x4 acc[2][2][4][2];
; #pragma unroll
;     for (int a = 0; a < 2; ++a)
; #pragma unroll
;         for (int b = 0; b < 2; ++b)
; #pragma unroll
;             for (int m = 0; m < 4; ++m)
; #pragma unroll
;                 for (int n = 0; n < 2; ++n) acc[a][b][m][n] = (f32x4){0.f, 0.f, 0.f, 0.f};
.Lpl143_zero:
	v_mov_b32_e32 v129, 0
	v_mov_b32_e32 v128, v129
	v_mov_b32_e32 v127, v129
	v_mov_b32_e32 v126, v129
	v_mov_b32_e32 v125, v129
	v_mov_b32_e32 v124, v129
	v_mov_b32_e32 v123, v129
	v_mov_b32_e32 v122, v129
	v_mov_b32_e32 v113, v129
	v_mov_b32_e32 v112, v129
	v_mov_b32_e32 v111, v129
	v_mov_b32_e32 v110, v129
	v_mov_b32_e32 v109, v129
	v_mov_b32_e32 v108, v129
	v_mov_b32_e32 v107, v129
	v_mov_b32_e32 v106, v129
	v_mov_b32_e32 v97, v129
	v_mov_b32_e32 v96, v129
	v_mov_b32_e32 v95, v129
	v_mov_b32_e32 v94, v129
	v_mov_b32_e32 v93, v129
	v_mov_b32_e32 v92, v129
	v_mov_b32_e32 v91, v129
	v_mov_b32_e32 v90, v129
	v_mov_b32_e32 v81, v129
	v_mov_b32_e32 v80, v129
	v_mov_b32_e32 v79, v129
	v_mov_b32_e32 v78, v129
	v_mov_b32_e32 v77, v129
	v_mov_b32_e32 v76, v129
	v_mov_b32_e32 v75, v129
	v_mov_b32_e32 v74, v129
	v_mov_b32_e32 v121, v129
	v_mov_b32_e32 v120, v129
	v_mov_b32_e32 v119, v129
	v_mov_b32_e32 v118, v129
	v_mov_b32_e32 v117, v129
	v_mov_b32_e32 v116, v129
	v_mov_b32_e32 v115, v129
	v_mov_b32_e32 v114, v129
	v_mov_b32_e32 v105, v129
	v_mov_b32_e32 v104, v129
	v_mov_b32_e32 v103, v129
	v_mov_b32_e32 v102, v129
	v_mov_b32_e32 v101, v129
	v_mov_b32_e32 v100, v129
	v_mov_b32_e32 v99, v129
	v_mov_b32_e32 v98, v129
	v_mov_b32_e32 v89, v129
	v_mov_b32_e32 v88, v129
	v_mov_b32_e32 v87, v129
	v_mov_b32_e32 v86, v129
	v_mov_b32_e32 v85, v129
	v_mov_b32_e32 v84, v129
	v_mov_b32_e32 v83, v129
	v_mov_b32_e32 v82, v129
	v_mov_b32_e32 v73, v129
	v_mov_b32_e32 v72, v129
	v_mov_b32_e32 v71, v129
	v_mov_b32_e32 v70, v129
	v_mov_b32_e32 v69, v129
	v_mov_b32_e32 v68, v129
	v_mov_b32_e32 v67, v129
	v_mov_b32_e32 v66, v129
	v_mov_b32_e32 v65, v129
	v_mov_b32_e32 v64, v129
	v_mov_b32_e32 v63, v129
	v_mov_b32_e32 v62, v129
	v_mov_b32_e32 v61, v129
	v_mov_b32_e32 v60, v129
	v_mov_b32_e32 v59, v129
	v_mov_b32_e32 v58, v129
	v_mov_b32_e32 v49, v129
	v_mov_b32_e32 v48, v129
	v_mov_b32_e32 v47, v129
	v_mov_b32_e32 v46, v129
	v_mov_b32_e32 v45, v129
	v_mov_b32_e32 v44, v129
	v_mov_b32_e32 v43, v129
	v_mov_b32_e32 v42, v129
	v_mov_b32_e32 v33, v129
	v_mov_b32_e32 v32, v129
	v_mov_b32_e32 v31, v129
	v_mov_b32_e32 v30, v129
	v_mov_b32_e32 v29, v129
	v_mov_b32_e32 v28, v129
	v_mov_b32_e32 v27, v129
	v_mov_b32_e32 v26, v129
	v_mov_b32_e32 v17, v129
	v_mov_b32_e32 v16, v129
	v_mov_b32_e32 v15, v129
	v_mov_b32_e32 v14, v129
	v_mov_b32_e32 v13, v129
	v_mov_b32_e32 v12, v129
	v_mov_b32_e32 v11, v129
	v_mov_b32_e32 v10, v129
	v_mov_b32_e32 v57, v129
	v_mov_b32_e32 v56, v129
	v_mov_b32_e32 v55, v129
	v_mov_b32_e32 v54, v129
	v_mov_b32_e32 v53, v129
	v_mov_b32_e32 v52, v129
	v_mov_b32_e32 v51, v129
	v_mov_b32_e32 v50, v129
	v_mov_b32_e32 v41, v129
	v_mov_b32_e32 v40, v129
	v_mov_b32_e32 v39, v129
	v_mov_b32_e32 v38, v129
	v_mov_b32_e32 v37, v129
	v_mov_b32_e32 v36, v129
	v_mov_b32_e32 v35, v129
	v_mov_b32_e32 v34, v129
	v_mov_b32_e32 v25, v129
	v_mov_b32_e32 v24, v129
	v_mov_b32_e32 v23, v129
	v_mov_b32_e32 v22, v129
	v_mov_b32_e32 v21, v129
	v_mov_b32_e32 v20, v129
	v_mov_b32_e32 v19, v129
	v_mov_b32_e32 v18, v129
	v_mov_b32_e32 v9, v129
	v_mov_b32_e32 v8, v129
	v_mov_b32_e32 v7, v129
	v_mov_b32_e32 v6, v129
	v_mov_b32_e32 v5, v129
	v_mov_b32_e32 v4, v129
	v_mov_b32_e32 v3, v129
	v_mov_b32_e32 v2, v129
	s_branch .LBB0_145

; template <class Epi, class Sched>
; __device__ __forceinline__ void gemm_phase(LAS unsigned char* lds, const Gemm g, const Sched S, const Epi E, const int tid) {
;     ...
;     f32x4 acc[2][2][4][2];
; #pragma unroll
;     for (int a = 0; a < 2; ++a)
; #pragma unroll
;         for (int b = 0; b < 2; ++b)
; #pragma unroll
;             for (int m = 0; m < 4; ++m)
; #pragma unroll
;                 for (int n = 0; n < 2; ++n) acc[a][b][m][n] = (f32x4){0.f, 0.f, 0.f, 0.f};
;     bf16x8 At[4][2], B0[2][2], B1[2][2];
;     const char* cA = (const char*)g.A + (size_t)cur.pm * tstepA; const char* cB = (const char*)g.Bt + (size_t)cur.pn * tstepB;
;     PG8_STAGE(PG8_SB(0, 0), cB, voffB); PG8_STAGE(PG8_SB(0, 1), cB + hstepB, voffB); PG8_STAGE(PG8_SA(0, 0), cA, voffA); PG8_STAGE(PG8_SA(0, 1), cA + hstepA, voffA);
;     if (wr == 1) PG8_BAR;
;     PG8_WAIT_V(2); PG8_BAR;
;     PG8_STAGE(PG8_SB(1, 0), cB + kstep, voffB); PG8_STAGE(PG8_SA(1, 0), cA + kstep, voffA); PG8_STAGE(PG8_SB(1, 1), cB + hstepB + kstep, voffB);
;     PG8_WAIT_V(6); PG8_BAR;
;     for (;;) {
;         const bool has_next = S.next(ui + 1, nxt);
;         const char* nA = has_next ? (const char*)g.A + (size_t)nxt.pm * tstepA : cA; const char* nB = has_next ? (const char*)g.Bt + (size_t)nxt.pn * tstepB : cB;
;         for (int t = 0; t < nt; t += 2) {
;             const bool last = (t == nt - 2);
;             const char* a1 = cA + (size_t)(t + 1) * kstep;
;             const char* a2 = last ? nA : cA + (size_t)(t + 2) * kstep; const char* b2 = last ? nB : cB + (size_t)(t + 2) * kstep;
;             const char* a3 = a2 + kstep; const char* b3 = b2 + kstep;
;             PG8_LDB(B0, 0, 0); PG8_LDB(B1, 0, 1); PG8_SCHED; PG8_LDA(At, 0, 0); PG8_STAGE(PG8_SA(1, 1), a1 + hstepA, voffA);
;             PG8_WAIT_V(8); PG8_WAIT_L(0); PG8_BAR; PG8_MMA(0, 0, At, B0); PG8_MMA(0, 1, At, B1); PG8_BAR; PG8_SCHED;
;             PG8_LDA(At, 0, 1); PG8_STAGE(PG8_SB(0, 0), b2, voffB); PG8_STAGE(PG8_SB(0, 1), b2 + hstepB, voffB); PG8_STAGE(PG8_SA(0, 0), a2, voffA);
;             PG8_WAIT_V(8); PG8_WAIT_L(0); PG8_BAR; PG8_MMA(1, 0, At, B0); PG8_MMA(1, 1, At, B1); PG8_BAR; PG8_SCHED;
;             PG8_LDB(B0, 1, 0); PG8_LDB(B1, 1, 1); PG8_SCHED; PG8_LDA(At, 1, 0); PG8_STAGE(PG8_SA(0, 1), a2 + hstepA, voffA);
;             PG8_WAIT_V(8); PG8_WAIT_L(0); PG8_BAR; PG8_MMA(0, 0, At, B0); PG8_MMA(0, 1, At, B1); PG8_BAR; PG8_SCHED;
.LBB0_546:
	s_ashr_i32 s53, s52, 31
	s_lshl_b64 s[12:13], s[52:53], 19
	s_add_u32 s64, s36, s12
	s_addc_u32 s65, s37, s13
	s_ashr_i32 s51, s50, 31
	s_lshl_b64 s[12:13], s[50:51], 19
	s_add_u32 s68, s61, s12
	s_addc_u32 s69, s70, s13
	s_andn2_b64 vcc, exec, s[10:11]
	s_cbranch_vccnz .Lpl548_zero
	s_and_b64 s[12:13], s[44:45], exec
	s_cselect_b32 s12, s65, s7
	s_cselect_b32 s13, s64, s6
	s_cselect_b32 s14, s69, s5
	s_cselect_b32 s15, s68, s4
	s_add_u32 s18, s4, 0x100
	s_addc_u32 s19, s5, 0
	s_add_u32 s4, s6, 0x40080
	v_mov_b32_e32 v2, 0
	s_addc_u32 s5, s7, 0
	s_mov_b32 s6, 0
	s_add_i32 s20, s6, 2
	s_add_u32 s7, s4, 0xfffc0080
	s_addc_u32 s16, s5, -1
	s_add_i32 s21, 0, 0x10000
	s_cmp_eq_u32 s80, s6
	s_cselect_b32 s17, s12, s16
	s_cselect_b32 s16, s13, s7
	v_add_u32_e32 v0, s21, v177
	s_cselect_b32 s7, s14, s19
	s_cselect_b32 s6, s15, s18
	s_add_i32 s24, 0, 0x14000
	ds_read_b128 v[150:153], v0
	ds_read_b128 v[154:157], v0 offset:1024
	ds_read_b128 v[158:161], v0 offset:2048
	ds_read_b128 v[162:165], v0 offset:3072
	v_add_u32_e32 v0, s24, v177
	ds_read_b128 v[166:169], v0
	ds_read_b128 v[170:173], v0 offset:1024
	ds_read_b128 v[180:183], v0 offset:2048
	ds_read_b128 v[184:187], v0 offset:3072
	v_lshl_add_u64 v[174:175], s[4:5], 0, v[148:149]
	s_add_i32 m0, s72, 0xc000
	ds_read_b128 v[206:209], v179
	ds_read_b128 v[232:235], v179 offset:1024
	ds_read_b128 v[236:239], v179 offset:2048
	ds_read_b128 v[240:243], v179 offset:3072
	ds_read_b128 v[244:247], v179 offset:4096
	ds_read_b128 v[248:251], v179 offset:5120
	ds_read_b128 v[188:191], v179 offset:6144
	ds_read_b128 v[218:221], v179 offset:7168
	global_load_lds_dwordx4 v[174:175], off
	v_lshl_add_u64 v[174:175], s[4:5], 0, v[146:147]
	s_add_i32 m0, s72, 0xe000
	s_nop 0
	global_load_lds_dwordx4 v[174:175], off
	s_waitcnt vmcnt(8)
	s_waitcnt lgkmcnt(0)
	s_barrier
	s_setprio 1
	s_waitcnt lgkmcnt(0)
	v_mfma_f32_16x16x32_bf16 v[126:129], v[150:153], v[206:209], 0
	v_mfma_f32_16x16x32_bf16 v[122:125], v[158:161], v[206:209], 0
	v_mfma_f32_16x16x32_bf16 v[110:113], v[150:153], v[236:239], 0
	v_mfma_f32_16x16x32_bf16 v[106:109], v[158:161], v[236:239], 0
	v_mfma_f32_16x16x32_bf16 v[94:97], v[150:153], v[244:247], 0
	v_mfma_f32_16x16x32_bf16 v[90:93], v[158:161], v[244:247], 0
	v_mfma_f32_16x16x32_bf16 v[78:81], v[150:153], v[188:191], 0
	v_mfma_f32_16x16x32_bf16 v[74:77], v[158:161], v[188:191], 0
	v_mfma_f32_16x16x32_bf16 v[126:129], v[154:157], v[232:235], v[126:129]
	v_mfma_f32_16x16x32_bf16 v[122:125], v[162:165], v[232:235], v[122:125]
	v_mfma_f32_16x16x32_bf16 v[110:113], v[154:157], v[240:243], v[110:113]
	v_mfma_f32_16x16x32_bf16 v[106:109], v[162:165], v[240:243], v[106:109]
	v_mfma_f32_16x16x32_bf16 v[94:97], v[154:157], v[248:251], v[94:97]
	v_mfma_f32_16x16x32_bf16 v[90:93], v[162:165], v[248:251], v[90:93]
	v_mfma_f32_16x16x32_bf16 v[78:81], v[154:157], v[218:221], v[78:81]
	v_mfma_f32_16x16x32_bf16 v[74:77], v[162:165], v[218:221], v[74:77]
	s_setprio 0
	s_setprio 1
	v_mfma_f32_16x16x32_bf16 v[118:121], v[166:169], v[206:209], 0
	v_mfma_f32_16x16x32_bf16 v[114:117], v[180:183], v[206:209], 0
	v_mfma_f32_16x16x32_bf16 v[102:105], v[166:169], v[236:239], 0
	v_mfma_f32_16x16x32_bf16 v[98:101], v[180:183], v[236:239], 0
	v_mfma_f32_16x16x32_bf16 v[86:89], v[166:169], v[244:247], 0
	v_mfma_f32_16x16x32_bf16 v[82:85], v[180:183], v[244:247], 0
	v_mfma_f32_16x16x32_bf16 v[70:73], v[166:169], v[188:191], 0
	v_mfma_f32_16x16x32_bf16 v[66:69], v[180:183], v[188:191], 0
	v_mfma_f32_16x16x32_bf16 v[118:121], v[170:173], v[232:235], v[118:121]
	v_mfma_f32_16x16x32_bf16 v[114:117], v[184:187], v[232:235], v[114:117]
	v_mfma_f32_16x16x32_bf16 v[102:105], v[170:173], v[240:243], v[102:105]
	v_mfma_f32_16x16x32_bf16 v[98:101], v[184:187], v[240:243], v[98:101]
	v_mfma_f32_16x16x32_bf16 v[86:89], v[170:173], v[248:251], v[86:89]
	v_mfma_f32_16x16x32_bf16 v[82:85], v[184:187], v[248:251], v[82:85]
	v_mfma_f32_16x16x32_bf16 v[70:73], v[170:173], v[218:221], v[70:73]
	v_mfma_f32_16x16x32_bf16 v[66:69], v[184:187], v[218:221], v[66:69]
	s_setprio 0
	s_barrier
	s_add_i32 s21, s21, s71
	v_lshl_add_u64 v[174:175], s[6:7], 0, v[132:133]
	s_mov_b32 m0, s21
	ds_read_b128 v[188:191], v179 offset:16384
	ds_read_b128 v[206:209], v179 offset:17408
	ds_read_b128 v[218:221], v179 offset:18432
	ds_read_b128 v[232:235], v179 offset:19456
	ds_read_b128 v[236:239], v179 offset:20480
	ds_read_b128 v[240:243], v179 offset:21504
	ds_read_b128 v[244:247], v179 offset:22528
	ds_read_b128 v[248:251], v179 offset:23552
	global_load_lds_dwordx4 v[174:175], off
	s_add_i32 m0, s21, 0x2000
	s_add_u32 s22, s6, 0x40000
	v_lshl_add_u64 v[192:193], s[6:7], 0, v[136:137]
	s_addc_u32 s23, s7, 0
	s_add_i32 s21, s24, s71
	global_load_lds_dwordx4 v[192:193], off
	v_lshl_add_u64 v[194:195], s[22:23], 0, v[132:133]
	s_mov_b32 m0, s21
	v_lshl_add_u64 v[210:211], s[16:17], 0, v[134:135]
	global_load_lds_dwordx4 v[194:195], off
	v_lshl_add_u64 v[194:195], s[22:23], 0, v[136:137]
	s_add_i32 m0, s21, 0x2000
	s_nop 0
	global_load_lds_dwordx4 v[194:195], off
	v_lshl_add_u64 v[194:195], s[16:17], 0, v[130:131]
	s_mov_b32 m0, s72
	s_nop 0
	global_load_lds_dwordx4 v[194:195], off
	s_mov_b32 m0, s73
	s_nop 0
	global_load_lds_dwordx4 v[210:211], off
	s_waitcnt vmcnt(8)
	s_waitcnt lgkmcnt(0)
	s_barrier
; #define PG8_STAGE(bufoff, gbase, voff) do { _Pragma("unroll") for (int _i = 0; _i < 2; ++_i) \
;         __builtin_amdgcn_global_load_lds((const unsigned*)((const char*)(gbase) + (voff)[_i]), (LAS unsigned*)(lds + (bufoff) + ldsw + _i * 8192), 16, 0, 0); } while (0)
; #define PG8_LDA(dst, b, h) do { _Pragma("unroll") for (int m = 0; m < 4; ++m) _Pragma("unroll") for (int k = 0; k < 2; ++k) dst[m][k] = *(const LAS bf16x8*)(lds + PG8_SA(b, h) + aoff + m * 2048 + k * 1024); } while (0)
; #define PG8_LDB(dst, b, h) do { _Pragma("unroll") for (int n = 0; n < 2; ++n) _Pragma("unroll") for (int k = 0; k < 2; ++k) dst[n][k] = *(const LAS bf16x8*)(lds + PG8_SB(b, h) + boff + n * 2048 + k * 1024); } while (0)
; #define PG8_MMA(ai, bj, At, Bt) do { __builtin_amdgcn_s_setprio(1); _Pragma("unroll") for (int m = 0; m < 4; ++m) _Pragma("unroll") for (int n = 0; n < 2; ++n) _Pragma("unroll") for (int k = 0; k < 2; ++k) \
;         acc[ai][bj][m][n] = __builtin_amdgcn_mfma_f32_16x16x32_bf16(Bt[n][k], At[m][k], acc[ai][bj][m][n], 0, 0, 0); __builtin_amdgcn_s_setprio(0); } while (0)
; #define PG8_WAIT_V(n) asm volatile("s_waitcnt vmcnt(" #n ")" ::: "memory")
; #define PG8_WAIT_L(n) asm volatile("s_waitcnt lgkmcnt(" #n ")" ::: "memory")
; #define PG8_BAR __builtin_amdgcn_s_barrier()
; #define PG8_SCHED __builtin_amdgcn_sched_barrier(0)
; #define PG8_LDA(dst, b, h) do { _Pragma("unroll") for (int m = 0; m < 4; ++m) _Pragma("unroll") for (int k = 0; k < 2; ++k) dst[m][k] = *(const LAS bf16x8*)(lds + PG8_SA(b, h) + aoff + m * 2048 + k * 1024); } while (0)
; template <class Epi, class Sched>
; __device__ __forceinline__ void gemm_phase(LAS unsigned char* lds, const Gemm g, const Sched S, const Epi E, const int tid) {
;     ...
;             PG8_WAIT_V(8); PG8_WAIT_L(0); PG8_BAR; PG8_MMA(0, 0, At, B0); PG8_MMA(0, 1, At, B1); PG8_BAR; PG8_SCHED;
;             PG8_LDA(At, 0, 1); PG8_STAGE(PG8_SB(0, 0), b2, voffB); PG8_STAGE(PG8_SB(0, 1), b2 + hstepB, voffB); PG8_STAGE(PG8_SA(0, 0), a2, voffA);
;             PG8_WAIT_V(8); PG8_WAIT_L(0); PG8_BAR; PG8_MMA(1, 0, At, B0); PG8_MMA(1, 1, At, B1); PG8_BAR; PG8_SCHED;
;             PG8_LDB(B0, 1, 0); PG8_LDB(B1, 1, 1); PG8_SCHED; PG8_LDA(At, 1, 0); PG8_STAGE(PG8_SA(0, 1), a2 + hstepA, voffA);
;             PG8_WAIT_V(8); PG8_WAIT_L(0); PG8_BAR; PG8_MMA(0, 0, At, B0); PG8_MMA(0, 1, At, B1); PG8_BAR; PG8_SCHED;
	s_setprio 1
	s_waitcnt lgkmcnt(0)
	v_mfma_f32_16x16x32_bf16 v[62:65], v[150:153], v[188:191], 0
	v_mfma_f32_16x16x32_bf16 v[58:61], v[158:161], v[188:191], 0
	v_mfma_f32_16x16x32_bf16 v[46:49], v[150:153], v[218:221], 0
	v_mfma_f32_16x16x32_bf16 v[42:45], v[158:161], v[218:221], 0
	v_mfma_f32_16x16x32_bf16 v[30:33], v[150:153], v[236:239], 0
	v_mfma_f32_16x16x32_bf16 v[26:29], v[158:161], v[236:239], 0
	v_mfma_f32_16x16x32_bf16 v[14:17], v[150:153], v[244:247], 0
	v_mfma_f32_16x16x32_bf16 v[10:13], v[158:161], v[244:247], 0
	v_mfma_f32_16x16x32_bf16 v[62:65], v[154:157], v[206:209], v[62:65]
	v_mfma_f32_16x16x32_bf16 v[58:61], v[162:165], v[206:209], v[58:61]
	v_mfma_f32_16x16x32_bf16 v[46:49], v[154:157], v[232:235], v[46:49]
	v_mfma_f32_16x16x32_bf16 v[42:45], v[162:165], v[232:235], v[42:45]
	v_mfma_f32_16x16x32_bf16 v[30:33], v[154:157], v[240:243], v[30:33]
	v_mfma_f32_16x16x32_bf16 v[26:29], v[162:165], v[240:243], v[26:29]
	v_mfma_f32_16x16x32_bf16 v[14:17], v[154:157], v[248:251], v[14:17]
	v_mfma_f32_16x16x32_bf16 v[10:13], v[162:165], v[248:251], v[10:13]
	s_setprio 0
	s_setprio 1
	v_mfma_f32_16x16x32_bf16 v[54:57], v[166:169], v[188:191], 0
	v_mfma_f32_16x16x32_bf16 v[50:53], v[180:183], v[188:191], 0
	v_mfma_f32_16x16x32_bf16 v[38:41], v[166:169], v[218:221], 0
	v_mfma_f32_16x16x32_bf16 v[34:37], v[180:183], v[218:221], 0
	v_mfma_f32_16x16x32_bf16 v[22:25], v[166:169], v[236:239], 0
	v_mfma_f32_16x16x32_bf16 v[18:21], v[180:183], v[236:239], 0
	v_mfma_f32_16x16x32_bf16 v[6:9], v[166:169], v[244:247], 0
	v_mfma_f32_16x16x32_bf16 v[2:5], v[180:183], v[244:247], 0
	v_mfma_f32_16x16x32_bf16 v[54:57], v[170:173], v[206:209], v[54:57]
	v_mfma_f32_16x16x32_bf16 v[50:53], v[184:187], v[206:209], v[50:53]
	v_mfma_f32_16x16x32_bf16 v[38:41], v[170:173], v[232:235], v[38:41]
	v_mfma_f32_16x16x32_bf16 v[34:37], v[184:187], v[232:235], v[34:37]
	v_mfma_f32_16x16x32_bf16 v[22:25], v[170:173], v[240:243], v[22:25]
	v_mfma_f32_16x16x32_bf16 v[18:21], v[184:187], v[240:243], v[18:21]
	v_mfma_f32_16x16x32_bf16 v[6:9], v[170:173], v[248:251], v[6:9]
	v_mfma_f32_16x16x32_bf16 v[2:5], v[184:187], v[248:251], v[2:5]
	s_setprio 0
	s_barrier
	s_add_i32 s21, 0, 0x18000
	v_add_u32_e32 v0, s21, v177
	s_add_i32 s22, 0, 0x1c000
	ds_read_b128 v[150:153], v0
	ds_read_b128 v[154:157], v0 offset:1024
	ds_read_b128 v[158:161], v0 offset:2048
	ds_read_b128 v[162:165], v0 offset:3072
	v_add_u32_e32 v0, s22, v177
	ds_read_b128 v[166:169], v0
	ds_read_b128 v[170:173], v0 offset:1024
	ds_read_b128 v[180:183], v0 offset:2048
	ds_read_b128 v[184:187], v0 offset:3072
	s_add_u32 s16, s16, 0x40000
	s_addc_u32 s17, s17, 0
	s_mov_b32 m0, s74
	v_lshl_add_u64 v[222:223], s[16:17], 0, v[130:131]
	ds_read_b128 v[188:191], v179 offset:32768
	ds_read_b128 v[206:209], v179 offset:33792
	ds_read_b128 v[218:221], v179 offset:34816
	ds_read_b128 v[232:235], v179 offset:35840
	ds_read_b128 v[236:239], v179 offset:36864
	ds_read_b128 v[240:243], v179 offset:37888
	ds_read_b128 v[244:247], v179 offset:38912
	ds_read_b128 v[248:251], v179 offset:39936
	global_load_lds_dwordx4 v[222:223], off
	v_lshl_add_u64 v[222:223], s[16:17], 0, v[134:135]
	s_mov_b32 m0, s75
	s_nop 0
	global_load_lds_dwordx4 v[222:223], off
	s_waitcnt vmcnt(8)
	s_waitcnt lgkmcnt(0)
	s_barrier
	s_setprio 1
	s_waitcnt lgkmcnt(0)
	v_mfma_f32_16x16x32_bf16 v[126:129], v[150:153], v[188:191], v[126:129]
	v_mfma_f32_16x16x32_bf16 v[122:125], v[158:161], v[188:191], v[122:125]
	v_mfma_f32_16x16x32_bf16 v[110:113], v[150:153], v[218:221], v[110:113]
	v_mfma_f32_16x16x32_bf16 v[106:109], v[158:161], v[218:221], v[106:109]
	v_mfma_f32_16x16x32_bf16 v[94:97], v[150:153], v[236:239], v[94:97]
	v_mfma_f32_16x16x32_bf16 v[90:93], v[158:161], v[236:239], v[90:93]
	v_mfma_f32_16x16x32_bf16 v[78:81], v[150:153], v[244:247], v[78:81]
	v_mfma_f32_16x16x32_bf16 v[74:77], v[158:161], v[244:247], v[74:77]
	v_mfma_f32_16x16x32_bf16 v[126:129], v[154:157], v[206:209], v[126:129]
	v_mfma_f32_16x16x32_bf16 v[122:125], v[162:165], v[206:209], v[122:125]
	v_mfma_f32_16x16x32_bf16 v[110:113], v[154:157], v[232:235], v[110:113]
	v_mfma_f32_16x16x32_bf16 v[106:109], v[162:165], v[232:235], v[106:109]
	v_mfma_f32_16x16x32_bf16 v[94:97], v[154:157], v[240:243], v[94:97]
	v_mfma_f32_16x16x32_bf16 v[90:93], v[162:165], v[240:243], v[90:93]
	v_mfma_f32_16x16x32_bf16 v[78:81], v[154:157], v[248:251], v[78:81]
	v_mfma_f32_16x16x32_bf16 v[74:77], v[162:165], v[248:251], v[74:77]
	s_setprio 0
	s_setprio 1
	v_mfma_f32_16x16x32_bf16 v[118:121], v[166:169], v[188:191], v[118:121]
	v_mfma_f32_16x16x32_bf16 v[114:117], v[180:183], v[188:191], v[114:117]
	v_mfma_f32_16x16x32_bf16 v[102:105], v[166:169], v[218:221], v[102:105]
	v_mfma_f32_16x16x32_bf16 v[98:101], v[180:183], v[218:221], v[98:101]
	v_mfma_f32_16x16x32_bf16 v[86:89], v[166:169], v[236:239], v[86:89]
	v_mfma_f32_16x16x32_bf16 v[82:85], v[180:183], v[236:239], v[82:85]
	v_mfma_f32_16x16x32_bf16 v[70:73], v[166:169], v[244:247], v[70:73]
	v_mfma_f32_16x16x32_bf16 v[66:69], v[180:183], v[244:247], v[66:69]
	v_mfma_f32_16x16x32_bf16 v[118:121], v[170:173], v[206:209], v[118:121]
	v_mfma_f32_16x16x32_bf16 v[114:117], v[184:187], v[206:209], v[114:117]
	v_mfma_f32_16x16x32_bf16 v[102:105], v[170:173], v[232:235], v[102:105]
	v_mfma_f32_16x16x32_bf16 v[98:101], v[184:187], v[232:235], v[98:101]
	v_mfma_f32_16x16x32_bf16 v[86:89], v[170:173], v[240:243], v[86:89]
	v_mfma_f32_16x16x32_bf16 v[82:85], v[184:187], v[240:243], v[82:85]
	v_mfma_f32_16x16x32_bf16 v[70:73], v[170:173], v[248:251], v[70:73]
	v_mfma_f32_16x16x32_bf16 v[66:69], v[184:187], v[248:251], v[66:69]
	s_setprio 0
	s_barrier
; #define PG8_STAGE(bufoff, gbase, voff) do { _Pragma("unroll") for (int _i = 0; _i < 2; ++_i) \
;         __builtin_amdgcn_global_load_lds((const unsigned*)((const char*)(gbase) + (voff)[_i]), (LAS unsigned*)(lds + (bufoff) + ldsw + _i * 8192), 16, 0, 0); } while (0)
; #define PG8_LDA(dst, b, h) do { _Pragma("unroll") for (int m = 0; m < 4; ++m) _Pragma("unroll") for (int k = 0; k < 2; ++k) dst[m][k] = *(const LAS bf16x8*)(lds + PG8_SA(b, h) + aoff + m * 2048 + k * 1024); } while (0)
; #define PG8_MMA(ai, bj, At, Bt) do { __builtin_amdgcn_s_setprio(1); _Pragma("unroll") for (int m = 0; m < 4; ++m) _Pragma("unroll") for (int n = 0; n < 2; ++n) _Pragma("unroll") for (int k = 0; k < 2; ++k) \
;         acc[ai][bj][m][n] = __builtin_amdgcn_mfma_f32_16x16x32_bf16(Bt[n][k], At[m][k], acc[ai][bj][m][n], 0, 0, 0); __builtin_amdgcn_s_setprio(0); } while (0)
; #define PG8_WAIT_V(n) asm volatile("s_waitcnt vmcnt(" #n ")" ::: "memory")
; #define PG8_WAIT_L(n) asm volatile("s_waitcnt lgkmcnt(" #n ")" ::: "memory")
; #define PG8_BAR __builtin_amdgcn_s_barrier()
; #define PG8_SCHED __builtin_amdgcn_sched_barrier(0)
; #define PG8_STAGE(bufoff, gbase, voff, q64) do { \
;         __builtin_amdgcn_global_load_lds((const unsigned*)((const char*)(gbase) + (voff)), (LAS unsigned*)(lds + (bufoff) + ldsw), 16, 0, 0); \
;         __builtin_amdgcn_global_load_lds((const unsigned*)((const char*)(gbase) + (q64) + (voff)), (LAS unsigned*)(lds + (bufoff) + ldsw + 8192), 16, 0, 0); } while (0)
; #define PG8_LDA(dst, b, h) do { _Pragma("unroll") for (int m = 0; m < 4; ++m) _Pragma("unroll") for (int k = 0; k < 2; ++k) dst[m][k] = *(const LAS bf16x8*)(lds + PG8_SA(b, h) + aoff + m * 2048 + k * 1024); } while (0)
; #define PG8_WAIT_V(n) asm volatile("s_waitcnt vmcnt(" #n ")" ::: "memory")
; #define PG8_WAIT_L(n) asm volatile("s_waitcnt lgkmcnt(" #n ")" ::: "memory")
; #define PG8_BAR __builtin_amdgcn_s_barrier()
; template <class Epi, class Sched>
; __device__ __forceinline__ void gemm_phase(LAS unsigned char* lds, const Gemm g, const Sched S, const Epi E, const int tid) {
;     ...
;             PG8_LDA(At, 1, 1); PG8_STAGE(PG8_SB(1, 0), b3, voffB); PG8_STAGE(PG8_SB(1, 1), b3 + hstepB, voffB); PG8_STAGE(PG8_SA(1, 0), a3, voffA);
;             PG8_WAIT_V(8); PG8_WAIT_L(0); PG8_BAR; PG8_MMA(1, 0, At, B0); PG8_MMA(1, 1, At, B1); PG8_BAR; PG8_SCHED;
;         }
	s_add_i32 s16, s21, s71
	v_lshl_add_u64 v[174:175], v[174:175], 0, s[0:1]
	s_mov_b32 m0, s16
	ds_read_b128 v[188:191], v179 offset:49152
	ds_read_b128 v[206:209], v179 offset:50176
	ds_read_b128 v[218:221], v179 offset:51200
	ds_read_b128 v[232:235], v179 offset:52224
	ds_read_b128 v[236:239], v179 offset:53248
	ds_read_b128 v[240:243], v179 offset:54272
	ds_read_b128 v[244:247], v179 offset:55296
	ds_read_b128 v[248:251], v179 offset:56320
	global_load_lds_dwordx4 v[174:175], off
	s_add_i32 m0, s16, 0x2000
	s_add_u32 s6, s6, 0x40080
	v_lshl_add_u64 v[174:175], v[192:193], 0, s[0:1]
	s_addc_u32 s7, s7, 0
	s_add_i32 s16, s22, s71
	global_load_lds_dwordx4 v[174:175], off
	v_lshl_add_u64 v[174:175], s[6:7], 0, v[132:133]
	s_mov_b32 m0, s16
	s_nop 0
	global_load_lds_dwordx4 v[174:175], off
	v_lshl_add_u64 v[174:175], s[6:7], 0, v[136:137]
	s_add_i32 m0, s16, 0x2000
	s_nop 0
	global_load_lds_dwordx4 v[174:175], off
	v_lshl_add_u64 v[174:175], v[194:195], 0, s[0:1]
	s_mov_b32 m0, s78
	s_nop 0
	global_load_lds_dwordx4 v[174:175], off
	v_lshl_add_u64 v[174:175], v[210:211], 0, s[0:1]
	s_mov_b32 m0, s79
	s_nop 0
	global_load_lds_dwordx4 v[174:175], off
	s_waitcnt vmcnt(8)
	s_waitcnt lgkmcnt(0)
	s_barrier
	s_setprio 1
	s_waitcnt lgkmcnt(0)
	v_mfma_f32_16x16x32_bf16 v[62:65], v[150:153], v[188:191], v[62:65]
	v_mfma_f32_16x16x32_bf16 v[58:61], v[158:161], v[188:191], v[58:61]
	v_mfma_f32_16x16x32_bf16 v[46:49], v[150:153], v[218:221], v[46:49]
	v_mfma_f32_16x16x32_bf16 v[42:45], v[158:161], v[218:221], v[42:45]
	v_mfma_f32_16x16x32_bf16 v[30:33], v[150:153], v[236:239], v[30:33]
	v_mfma_f32_16x16x32_bf16 v[26:29], v[158:161], v[236:239], v[26:29]
	v_mfma_f32_16x16x32_bf16 v[14:17], v[150:153], v[244:247], v[14:17]
	v_mfma_f32_16x16x32_bf16 v[10:13], v[158:161], v[244:247], v[10:13]
	v_mfma_f32_16x16x32_bf16 v[62:65], v[154:157], v[206:209], v[62:65]
	v_mfma_f32_16x16x32_bf16 v[58:61], v[162:165], v[206:209], v[58:61]
	v_mfma_f32_16x16x32_bf16 v[46:49], v[154:157], v[232:235], v[46:49]
	v_mfma_f32_16x16x32_bf16 v[42:45], v[162:165], v[232:235], v[42:45]
	v_mfma_f32_16x16x32_bf16 v[30:33], v[154:157], v[240:243], v[30:33]
	v_mfma_f32_16x16x32_bf16 v[26:29], v[162:165], v[240:243], v[26:29]
	v_mfma_f32_16x16x32_bf16 v[14:17], v[154:157], v[248:251], v[14:17]
	v_mfma_f32_16x16x32_bf16 v[10:13], v[162:165], v[248:251], v[10:13]
	s_setprio 0
	s_setprio 1
	v_mfma_f32_16x16x32_bf16 v[54:57], v[166:169], v[188:191], v[54:57]
	v_mfma_f32_16x16x32_bf16 v[50:53], v[180:183], v[188:191], v[50:53]
	v_mfma_f32_16x16x32_bf16 v[38:41], v[166:169], v[218:221], v[38:41]
	v_mfma_f32_16x16x32_bf16 v[34:37], v[180:183], v[218:221], v[34:37]
	v_mfma_f32_16x16x32_bf16 v[22:25], v[166:169], v[236:239], v[22:25]
	v_mfma_f32_16x16x32_bf16 v[18:21], v[180:183], v[236:239], v[18:21]
	v_mfma_f32_16x16x32_bf16 v[6:9], v[166:169], v[244:247], v[6:9]
	v_mfma_f32_16x16x32_bf16 v[2:5], v[180:183], v[244:247], v[2:5]
	v_mfma_f32_16x16x32_bf16 v[54:57], v[170:173], v[206:209], v[54:57]
	v_mfma_f32_16x16x32_bf16 v[50:53], v[184:187], v[206:209], v[50:53]
	v_mfma_f32_16x16x32_bf16 v[38:41], v[170:173], v[232:235], v[38:41]
	v_mfma_f32_16x16x32_bf16 v[34:37], v[184:187], v[232:235], v[34:37]
	v_mfma_f32_16x16x32_bf16 v[22:25], v[170:173], v[240:243], v[22:25]
	v_mfma_f32_16x16x32_bf16 v[18:21], v[184:187], v[240:243], v[18:21]
	v_mfma_f32_16x16x32_bf16 v[6:9], v[170:173], v[248:251], v[6:9]
	v_mfma_f32_16x16x32_bf16 v[2:5], v[184:187], v[248:251], v[2:5]
	s_setprio 0
	s_barrier
	s_add_u32 s18, s18, 0x100
	s_addc_u32 s19, s19, 0
	s_add_u32 s4, s4, 0x100
	s_addc_u32 s5, s5, 0
	s_cmp_ge_i32 s20, s77
	s_mov_b32 s6, s20
	s_cbranch_scc1 .Lpl548_exit

; #define PG8_BAR __builtin_amdgcn_s_barrier()
; #define PG8_BAR __builtin_amdgcn_s_barrier()
; template <class Epi, class Sched>
; __device__ __forceinline__ void gemm_phase(LAS unsigned char* lds, const Gemm g, const Sched S, const Epi E, const int tid) {
;     ...
;         if (wr == 0) PG8_BAR;
.Lpl548_exit:
.LBB0_549:
	s_and_b64 vcc, exec, s[46:47]
	s_cbranch_vccz .LBB0_551
	s_barrier

; __device__ __forceinline__ float row_rs16(const float* ssq_x, int row) {
;     const f32x4* p = (const f32x4*)(ssq_x + (size_t)row * 16); const f32x4 a = p[0], b = p[1], c = p[2], d = p[3];
;     return rsqrtf((((a[0] + a[1]) + (a[2] + a[3])) + ((b[0] + b[1]) + (b[2] + b[3])) + ((c[0] + c[1]) + (c[2] + c[3])) + ((d[0] + d[1]) + (d[2] + d[3]))) * (1.0f / DM) + EPS);
; }
.LBB0_921:
	s_andn2_b64 vcc, exec, s[42:43]
	s_mov_b64 s[4:5], -1
	s_cbranch_vccnz .LBB0_870
	s_branch .LBB0_988
.Ltramp_233:
	s_branch .LBB0_233
.LBB0_922:
	s_and_b64 vcc, exec, s[4:5]
	s_cbranch_vccz .LBB0_921
	s_lshl_b32 s12, s76, 8
	s_cmp_lg_u32 s76, s3
	v_add_u32_e32 v131, s68, v0
	s_cselect_b64 s[20:21], -1, 0
	v_add_u32_e32 v134, s12, v131
	s_mov_b64 s[4:5], -1
	s_and_b64 vcc, exec, s[20:21]
	s_cbranch_vccz .LBB0_929
	s_cmp_lg_u32 s76, s62
	s_cbranch_scc0 .LBB0_926
	v_ashrrev_i32_e32 v135, 31, v134
	v_readlane_b32 s4, v254, 48
	v_lshlrev_b64 v[136:137], 6, v[134:135]
	v_readlane_b32 s5, v254, 49
	s_nop 1
	v_lshl_add_u64 v[148:149], s[4:5], 0, v[136:137]
	flat_load_dwordx4 v[136:139], v[148:149]
	flat_load_dwordx4 v[140:143], v[148:149] offset:16
	flat_load_dwordx4 v[144:147], v[148:149] offset:32
	flat_load_dwordx4 v[158:161], v[148:149] offset:48
	s_mov_b64 s[4:5], 0
	s_waitcnt vmcnt(0) lgkmcnt(0)
	v_mov_b32_e32 v148, v137
	v_mov_b32_e32 v149, v138
	v_mov_b32_e32 v137, v139
	v_mov_b32_e32 v138, v141
	v_mov_b32_e32 v139, v142
	v_mov_b32_e32 v141, v143
	v_pk_add_f32 v[136:137], v[148:149], v[136:137]
	v_pk_add_f32 v[138:139], v[138:139], v[140:141]
	v_pk_add_f32 v[136:137], v[136:137], v[136:137] op_sel:[0,1] op_sel_hi:[1,0]
	v_pk_add_f32 v[138:139], v[138:139], v[138:139] op_sel:[0,1] op_sel_hi:[1,0]
	v_add_f32_e32 v140, v144, v145
	v_add_f32_e32 v142, v146, v147
	v_mov_b32_e32 v137, v158
	v_mov_b32_e32 v139, v159
	v_mov_b32_e32 v141, v160
	v_mov_b32_e32 v143, v161
	v_pk_add_f32 v[136:137], v[136:137], v[138:139]
	v_pk_add_f32 v[138:139], v[140:141], v[142:143]
	s_nop 0
	v_pk_add_f32 v[136:137], v[136:137], v[138:139]
	s_nop 0
	v_add_f32_e32 v0, v136, v137
	v_fmamk_f32 v0, v0, 0x3a800000, v205
	v_cmp_gt_f32_e32 vcc, s77, v0
	v_mul_f32_e32 v135, 0x4b800000, v0
	s_nop 0
	v_cndmask_b32_e32 v0, v0, v135, vcc
	v_rsq_f32_e32 v0, v0
	s_nop 0
	v_mul_f32_e32 v135, 0x45800000, v0
	v_cndmask_b32_e32 v0, v0, v135, vcc

; #define PG8_LDA(dst, b, h) do { _Pragma("unroll") for (int m = 0; m < 4; ++m) _Pragma("unroll") for (int k = 0; k < 2; ++k) dst[m][k] = *(const LAS bf16x8*)(lds + PG8_SA(b, h) + aoff + m * 2048 + k * 1024); } while (0)
; template <class Epi, class Sched>
; __device__ __forceinline__ void gemm_phase(LAS unsigned char* lds, const Gemm g, const Sched S, const Epi E, const int tid) {
;     ...
;     f32x4 acc[2][2][4][2];
; #pragma unroll
;     for (int a = 0; a < 2; ++a)
; #pragma unroll
;         for (int b = 0; b < 2; ++b)
; #pragma unroll
;             for (int m = 0; m < 4; ++m)
; #pragma unroll
;                 for (int n = 0; n < 2; ++n) acc[a][b][m][n] = (f32x4){0.f, 0.f, 0.f, 0.f};
;     bf16x8 At[4][2], B0[2][2], B1[2][2];
;     const char* cA = (const char*)g.A + (size_t)cur.pm * tstepA; const char* cB = (const char*)g.Bt + (size_t)cur.pn * tstepB;
;     PG8_STAGE(PG8_SB(0, 0), cB, voffB); PG8_STAGE(PG8_SB(0, 1), cB + hstepB, voffB); PG8_STAGE(PG8_SA(0, 0), cA, voffA); PG8_STAGE(PG8_SA(0, 1), cA + hstepA, voffA);
;     if (wr == 1) PG8_BAR;
;     PG8_WAIT_V(2); PG8_BAR;
;     PG8_STAGE(PG8_SB(1, 0), cB + kstep, voffB); PG8_STAGE(PG8_SA(1, 0), cA + kstep, voffA); PG8_STAGE(PG8_SB(1, 1), cB + hstepB + kstep, voffB);
;     PG8_WAIT_V(6); PG8_BAR;
;     for (;;) {
;         const bool has_next = S.next(ui + 1, nxt);
;         const char* nA = has_next ? (const char*)g.A + (size_t)nxt.pm * tstepA : cA; const char* nB = has_next ? (const char*)g.Bt + (size_t)nxt.pn * tstepB : cB;
;         for (int t = 0; t < nt; t += 2) {
;             const bool last = (t == nt - 2);
;             const char* a1 = cA + (size_t)(t + 1) * kstep;
;             const char* a2 = last ? nA : cA + (size_t)(t + 2) * kstep; const char* b2 = last ? nB : cB + (size_t)(t + 2) * kstep;
;             const char* a3 = a2 + kstep; const char* b3 = b2 + kstep;
;             PG8_LDB(B0, 0, 0); PG8_LDB(B1, 0, 1); PG8_SCHED; PG8_LDA(At, 0, 0); PG8_STAGE(PG8_SA(1, 1), a1 + hstepA, voffA);
;             PG8_WAIT_V(8); PG8_WAIT_L(0); PG8_BAR; PG8_MMA(0, 0, At, B0); PG8_MMA(0, 1, At, B1); PG8_BAR; PG8_SCHED;
;             PG8_LDA(At, 0, 1); PG8_STAGE(PG8_SB(0, 0), b2, voffB); PG8_STAGE(PG8_SB(0, 1), b2 + hstepB, voffB); PG8_STAGE(PG8_SA(0, 0), a2, voffA);
;             PG8_WAIT_V(8); PG8_WAIT_L(0); PG8_BAR; PG8_MMA(1, 0, At, B0); PG8_MMA(1, 1, At, B1); PG8_BAR; PG8_SCHED;
.LBB0_1098:
	s_andn2_b64 vcc, exec, s[42:43]
	s_waitcnt lgkmcnt(0)
	s_cbranch_vccnz .Lpl1100_zero
	s_add_u32 s38, s24, 0x100
	s_addc_u32 s39, s25, 0
	s_add_u32 s24, s28, 0x80
	v_mov_b32_e32 v2, 0
	s_addc_u32 s25, s29, 0
	s_mov_b32 s28, 0
	s_add_i32 s40, s28, 2
	s_add_u32 s41, s24, 0x80
	s_addc_u32 s29, s25, 0
	s_add_i32 s50, 0, 0x10000
	s_cmp_eq_u32 s56, s28
	s_cselect_b32 s29, s9, s29
	s_cselect_b32 s28, s8, s41
	v_add_u32_e32 v0, s50, v152
	s_cselect_b32 s49, s47, s39
	s_cselect_b32 s48, s46, s38
	s_add_i32 s41, 0, 0x14000
	ds_read_b128 v[148:151], v0
	ds_read_b128 v[154:157], v0 offset:1024
	ds_read_b128 v[158:161], v0 offset:2048
	ds_read_b128 v[162:165], v0 offset:3072
	v_add_u32_e32 v0, s41, v152
	ds_read_b128 v[166:169], v0
	ds_read_b128 v[170:173], v0 offset:1024
	ds_read_b128 v[174:177], v0 offset:2048
	ds_read_b128 v[178:181], v0 offset:3072
	v_lshl_add_u64 v[190:191], s[24:25], 0, v[146:147]
	s_add_i32 m0, s18, 0xc000
	ds_read_b128 v[182:185], v153
	ds_read_b128 v[186:189], v153 offset:1024
	ds_read_b128 v[206:209], v153 offset:2048
	ds_read_b128 v[232:235], v153 offset:3072
	ds_read_b128 v[236:239], v153 offset:4096
	ds_read_b128 v[240:243], v153 offset:5120
	ds_read_b128 v[244:247], v153 offset:6144
	ds_read_b128 v[248:251], v153 offset:7168
	global_load_lds_dwordx4 v[190:191], off
	v_lshl_add_u64 v[190:191], s[24:25], 0, v[144:145]
	s_add_i32 m0, s18, 0xe000
	s_nop 0
	global_load_lds_dwordx4 v[190:191], off
	s_waitcnt vmcnt(8)
	s_waitcnt lgkmcnt(0)
	s_barrier
	s_setprio 1
	s_waitcnt lgkmcnt(0)
	v_mfma_f32_16x16x32_bf16 v[122:125], v[148:151], v[182:185], 0
	v_mfma_f32_16x16x32_bf16 v[126:129], v[158:161], v[182:185], 0
	v_mfma_f32_16x16x32_bf16 v[110:113], v[148:151], v[206:209], 0
	v_mfma_f32_16x16x32_bf16 v[106:109], v[158:161], v[206:209], 0
	v_mfma_f32_16x16x32_bf16 v[94:97], v[148:151], v[236:239], 0
	v_mfma_f32_16x16x32_bf16 v[90:93], v[158:161], v[236:239], 0
	v_mfma_f32_16x16x32_bf16 v[78:81], v[148:151], v[244:247], 0
	v_mfma_f32_16x16x32_bf16 v[74:77], v[158:161], v[244:247], 0
	v_mfma_f32_16x16x32_bf16 v[122:125], v[154:157], v[186:189], v[122:125]
	v_mfma_f32_16x16x32_bf16 v[126:129], v[162:165], v[186:189], v[126:129]
	v_mfma_f32_16x16x32_bf16 v[110:113], v[154:157], v[232:235], v[110:113]
	v_mfma_f32_16x16x32_bf16 v[106:109], v[162:165], v[232:235], v[106:109]
	v_mfma_f32_16x16x32_bf16 v[94:97], v[154:157], v[240:243], v[94:97]
	v_mfma_f32_16x16x32_bf16 v[90:93], v[162:165], v[240:243], v[90:93]
	v_mfma_f32_16x16x32_bf16 v[78:81], v[154:157], v[248:251], v[78:81]
	v_mfma_f32_16x16x32_bf16 v[74:77], v[162:165], v[248:251], v[74:77]
	s_setprio 0
	s_setprio 1
	v_mfma_f32_16x16x32_bf16 v[118:121], v[166:169], v[182:185], 0
	v_mfma_f32_16x16x32_bf16 v[114:117], v[174:177], v[182:185], 0
	v_mfma_f32_16x16x32_bf16 v[102:105], v[166:169], v[206:209], 0
	v_mfma_f32_16x16x32_bf16 v[98:101], v[174:177], v[206:209], 0
	v_mfma_f32_16x16x32_bf16 v[86:89], v[166:169], v[236:239], 0
	v_mfma_f32_16x16x32_bf16 v[82:85], v[174:177], v[236:239], 0
	v_mfma_f32_16x16x32_bf16 v[70:73], v[166:169], v[244:247], 0
	v_mfma_f32_16x16x32_bf16 v[66:69], v[174:177], v[244:247], 0
	v_mfma_f32_16x16x32_bf16 v[118:121], v[170:173], v[186:189], v[118:121]
	v_mfma_f32_16x16x32_bf16 v[114:117], v[178:181], v[186:189], v[114:117]
	v_mfma_f32_16x16x32_bf16 v[102:105], v[170:173], v[232:235], v[102:105]
	v_mfma_f32_16x16x32_bf16 v[98:101], v[178:181], v[232:235], v[98:101]
	v_mfma_f32_16x16x32_bf16 v[86:89], v[170:173], v[240:243], v[86:89]
	v_mfma_f32_16x16x32_bf16 v[82:85], v[178:181], v[240:243], v[82:85]
	v_mfma_f32_16x16x32_bf16 v[70:73], v[170:173], v[248:251], v[70:73]
	v_mfma_f32_16x16x32_bf16 v[66:69], v[178:181], v[248:251], v[66:69]
	s_setprio 0
	s_barrier
	s_add_i32 s50, s50, s15
	v_lshl_add_u64 v[190:191], s[48:49], 0, v[136:137]
	s_mov_b32 m0, s50
	ds_read_b128 v[182:185], v153 offset:16384
	ds_read_b128 v[186:189], v153 offset:17408
	ds_read_b128 v[206:209], v153 offset:18432
	ds_read_b128 v[232:235], v153 offset:19456
	ds_read_b128 v[236:239], v153 offset:20480
	ds_read_b128 v[240:243], v153 offset:21504
	ds_read_b128 v[244:247], v153 offset:22528
	ds_read_b128 v[248:251], v153 offset:23552
	global_load_lds_dwordx4 v[190:191], off
	s_add_i32 m0, s50, 0x2000
	v_lshl_add_u64 v[210:211], s[48:49], 0, v[132:133]
	s_add_u32 s48, s48, s22
	s_addc_u32 s49, s49, s23
	s_add_i32 s41, s41, s15
	global_load_lds_dwordx4 v[210:211], off
	v_lshl_add_u64 v[218:219], s[48:49], 0, v[136:137]
	s_mov_b32 m0, s41
	v_lshl_add_u64 v[220:221], s[48:49], 0, v[132:133]
	global_load_lds_dwordx4 v[218:219], off
	s_add_i32 m0, s41, 0x2000
	v_lshl_add_u64 v[192:193], s[28:29], 0, v[138:139]
	global_load_lds_dwordx4 v[220:221], off
	s_mov_b32 m0, s18
	v_lshl_add_u64 v[222:223], s[28:29], 0, v[134:135]
	global_load_lds_dwordx4 v[192:193], off
	s_mov_b32 m0, s19
	s_nop 0
	global_load_lds_dwordx4 v[222:223], off
	s_waitcnt vmcnt(8)
	s_waitcnt lgkmcnt(0)
	s_barrier
; #define PG8_STAGE(bufoff, gbase, voff) do { _Pragma("unroll") for (int _i = 0; _i < 2; ++_i) \
;         __builtin_amdgcn_global_load_lds((const unsigned*)((const char*)(gbase) + (voff)[_i]), (LAS unsigned*)(lds + (bufoff) + ldsw + _i * 8192), 16, 0, 0); } while (0)
; #define PG8_LDA(dst, b, h) do { _Pragma("unroll") for (int m = 0; m < 4; ++m) _Pragma("unroll") for (int k = 0; k < 2; ++k) dst[m][k] = *(const LAS bf16x8*)(lds + PG8_SA(b, h) + aoff + m * 2048 + k * 1024); } while (0)
; #define PG8_LDB(dst, b, h) do { _Pragma("unroll") for (int n = 0; n < 2; ++n) _Pragma("unroll") for (int k = 0; k < 2; ++k) dst[n][k] = *(const LAS bf16x8*)(lds + PG8_SB(b, h) + boff + n * 2048 + k * 1024); } while (0)
; #define PG8_MMA(ai, bj, At, Bt) do { __builtin_amdgcn_s_setprio(1); _Pragma("unroll") for (int m = 0; m < 4; ++m) _Pragma("unroll") for (int n = 0; n < 2; ++n) _Pragma("unroll") for (int k = 0; k < 2; ++k) \
;         acc[ai][bj][m][n] = __builtin_amdgcn_mfma_f32_16x16x32_bf16(Bt[n][k], At[m][k], acc[ai][bj][m][n], 0, 0, 0); __builtin_amdgcn_s_setprio(0); } while (0)
; #define PG8_WAIT_V(n) asm volatile("s_waitcnt vmcnt(" #n ")" ::: "memory")
; #define PG8_WAIT_L(n) asm volatile("s_waitcnt lgkmcnt(" #n ")" ::: "memory")
; #define PG8_BAR __builtin_amdgcn_s_barrier()
; #define PG8_SCHED __builtin_amdgcn_sched_barrier(0)
; #define PG8_LDA(dst, b, h) do { _Pragma("unroll") for (int m = 0; m < 4; ++m) _Pragma("unroll") for (int k = 0; k < 2; ++k) dst[m][k] = *(const LAS bf16x8*)(lds + PG8_SA(b, h) + aoff + m * 2048 + k * 1024); } while (0)
; template <class Epi, class Sched>
; __device__ __forceinline__ void gemm_phase(LAS unsigned char* lds, const Gemm g, const Sched S, const Epi E, const int tid) {
;     ...
;             PG8_WAIT_V(8); PG8_WAIT_L(0); PG8_BAR; PG8_MMA(0, 0, At, B0); PG8_MMA(0, 1, At, B1); PG8_BAR; PG8_SCHED;
;             PG8_LDA(At, 0, 1); PG8_STAGE(PG8_SB(0, 0), b2, voffB); PG8_STAGE(PG8_SB(0, 1), b2 + hstepB, voffB); PG8_STAGE(PG8_SA(0, 0), a2, voffA);
;             PG8_WAIT_V(8); PG8_WAIT_L(0); PG8_BAR; PG8_MMA(1, 0, At, B0); PG8_MMA(1, 1, At, B1); PG8_BAR; PG8_SCHED;
;             PG8_LDB(B0, 1, 0); PG8_LDB(B1, 1, 1); PG8_SCHED; PG8_LDA(At, 1, 0); PG8_STAGE(PG8_SA(0, 1), a2 + hstepA, voffA);
;             PG8_WAIT_V(8); PG8_WAIT_L(0); PG8_BAR; PG8_MMA(0, 0, At, B0); PG8_MMA(0, 1, At, B1); PG8_BAR; PG8_SCHED;
	s_setprio 1
	s_waitcnt lgkmcnt(0)
	v_mfma_f32_16x16x32_bf16 v[62:65], v[148:151], v[182:185], 0
	v_mfma_f32_16x16x32_bf16 v[58:61], v[158:161], v[182:185], 0
	v_mfma_f32_16x16x32_bf16 v[46:49], v[148:151], v[206:209], 0
	v_mfma_f32_16x16x32_bf16 v[42:45], v[158:161], v[206:209], 0
	v_mfma_f32_16x16x32_bf16 v[30:33], v[148:151], v[236:239], 0
	v_mfma_f32_16x16x32_bf16 v[26:29], v[158:161], v[236:239], 0
	v_mfma_f32_16x16x32_bf16 v[14:17], v[148:151], v[244:247], 0
	v_mfma_f32_16x16x32_bf16 v[10:13], v[158:161], v[244:247], 0
	v_mfma_f32_16x16x32_bf16 v[62:65], v[154:157], v[186:189], v[62:65]
	v_mfma_f32_16x16x32_bf16 v[58:61], v[162:165], v[186:189], v[58:61]
	v_mfma_f32_16x16x32_bf16 v[46:49], v[154:157], v[232:235], v[46:49]
	v_mfma_f32_16x16x32_bf16 v[42:45], v[162:165], v[232:235], v[42:45]
	v_mfma_f32_16x16x32_bf16 v[30:33], v[154:157], v[240:243], v[30:33]
	v_mfma_f32_16x16x32_bf16 v[26:29], v[162:165], v[240:243], v[26:29]
	v_mfma_f32_16x16x32_bf16 v[14:17], v[154:157], v[248:251], v[14:17]
	v_mfma_f32_16x16x32_bf16 v[10:13], v[162:165], v[248:251], v[10:13]
	s_setprio 0
	s_setprio 1
	v_mfma_f32_16x16x32_bf16 v[54:57], v[166:169], v[182:185], 0
	v_mfma_f32_16x16x32_bf16 v[50:53], v[174:177], v[182:185], 0
	v_mfma_f32_16x16x32_bf16 v[38:41], v[166:169], v[206:209], 0
	v_mfma_f32_16x16x32_bf16 v[34:37], v[174:177], v[206:209], 0
	v_mfma_f32_16x16x32_bf16 v[22:25], v[166:169], v[236:239], 0
	v_mfma_f32_16x16x32_bf16 v[18:21], v[174:177], v[236:239], 0
	v_mfma_f32_16x16x32_bf16 v[6:9], v[166:169], v[244:247], 0
	v_mfma_f32_16x16x32_bf16 v[2:5], v[174:177], v[244:247], 0
	v_mfma_f32_16x16x32_bf16 v[54:57], v[170:173], v[186:189], v[54:57]
	v_mfma_f32_16x16x32_bf16 v[50:53], v[178:181], v[186:189], v[50:53]
	v_mfma_f32_16x16x32_bf16 v[38:41], v[170:173], v[232:235], v[38:41]
	v_mfma_f32_16x16x32_bf16 v[34:37], v[178:181], v[232:235], v[34:37]
	v_mfma_f32_16x16x32_bf16 v[22:25], v[170:173], v[240:243], v[22:25]
	v_mfma_f32_16x16x32_bf16 v[18:21], v[178:181], v[240:243], v[18:21]
	v_mfma_f32_16x16x32_bf16 v[6:9], v[170:173], v[248:251], v[6:9]
	v_mfma_f32_16x16x32_bf16 v[2:5], v[178:181], v[248:251], v[2:5]
	s_setprio 0
	s_barrier
	s_add_i32 s41, 0, 0x18000
	v_add_u32_e32 v0, s41, v152
	s_add_i32 s48, 0, 0x1c000
	ds_read_b128 v[148:151], v0
	ds_read_b128 v[154:157], v0 offset:1024
	ds_read_b128 v[158:161], v0 offset:2048
	ds_read_b128 v[162:165], v0 offset:3072
	v_add_u32_e32 v0, s48, v152
	ds_read_b128 v[166:169], v0
	ds_read_b128 v[170:173], v0 offset:1024
	ds_read_b128 v[174:177], v0 offset:2048
	ds_read_b128 v[178:181], v0 offset:3072
	s_add_u32 s28, s28, s22
	s_addc_u32 s29, s29, s23
	s_mov_b32 m0, s31
	v_lshl_add_u64 v[194:195], s[28:29], 0, v[138:139]
	ds_read_b128 v[182:185], v153 offset:32768
	ds_read_b128 v[186:189], v153 offset:33792
	ds_read_b128 v[206:209], v153 offset:34816
	ds_read_b128 v[232:235], v153 offset:35840
	ds_read_b128 v[236:239], v153 offset:36864
	ds_read_b128 v[240:243], v153 offset:37888
	ds_read_b128 v[244:247], v153 offset:38912
	ds_read_b128 v[248:251], v153 offset:39936
	global_load_lds_dwordx4 v[194:195], off
	v_lshl_add_u64 v[194:195], s[28:29], 0, v[134:135]
	s_mov_b32 m0, s34
	s_nop 0
	global_load_lds_dwordx4 v[194:195], off
	s_waitcnt vmcnt(8)
	s_waitcnt lgkmcnt(0)
	s_barrier
	s_setprio 1
	s_waitcnt lgkmcnt(0)
	v_mfma_f32_16x16x32_bf16 v[122:125], v[148:151], v[182:185], v[122:125]
	v_mfma_f32_16x16x32_bf16 v[126:129], v[158:161], v[182:185], v[126:129]
	v_mfma_f32_16x16x32_bf16 v[110:113], v[148:151], v[206:209], v[110:113]
	v_mfma_f32_16x16x32_bf16 v[106:109], v[158:161], v[206:209], v[106:109]
	v_mfma_f32_16x16x32_bf16 v[94:97], v[148:151], v[236:239], v[94:97]
	v_mfma_f32_16x16x32_bf16 v[90:93], v[158:161], v[236:239], v[90:93]
	v_mfma_f32_16x16x32_bf16 v[78:81], v[148:151], v[244:247], v[78:81]
	v_mfma_f32_16x16x32_bf16 v[74:77], v[158:161], v[244:247], v[74:77]
	v_mfma_f32_16x16x32_bf16 v[122:125], v[154:157], v[186:189], v[122:125]
	v_mfma_f32_16x16x32_bf16 v[126:129], v[162:165], v[186:189], v[126:129]
	v_mfma_f32_16x16x32_bf16 v[110:113], v[154:157], v[232:235], v[110:113]
	v_mfma_f32_16x16x32_bf16 v[106:109], v[162:165], v[232:235], v[106:109]
	v_mfma_f32_16x16x32_bf16 v[94:97], v[154:157], v[240:243], v[94:97]
	v_mfma_f32_16x16x32_bf16 v[90:93], v[162:165], v[240:243], v[90:93]
	v_mfma_f32_16x16x32_bf16 v[78:81], v[154:157], v[248:251], v[78:81]
	v_mfma_f32_16x16x32_bf16 v[74:77], v[162:165], v[248:251], v[74:77]
	s_setprio 0
	s_setprio 1
	v_mfma_f32_16x16x32_bf16 v[118:121], v[166:169], v[182:185], v[118:121]
	v_mfma_f32_16x16x32_bf16 v[114:117], v[174:177], v[182:185], v[114:117]
	v_mfma_f32_16x16x32_bf16 v[102:105], v[166:169], v[206:209], v[102:105]
	v_mfma_f32_16x16x32_bf16 v[98:101], v[174:177], v[206:209], v[98:101]
	v_mfma_f32_16x16x32_bf16 v[86:89], v[166:169], v[236:239], v[86:89]
	v_mfma_f32_16x16x32_bf16 v[82:85], v[174:177], v[236:239], v[82:85]
	v_mfma_f32_16x16x32_bf16 v[70:73], v[166:169], v[244:247], v[70:73]
	v_mfma_f32_16x16x32_bf16 v[66:69], v[174:177], v[244:247], v[66:69]
	v_mfma_f32_16x16x32_bf16 v[118:121], v[170:173], v[186:189], v[118:121]
	v_mfma_f32_16x16x32_bf16 v[114:117], v[178:181], v[186:189], v[114:117]
	v_mfma_f32_16x16x32_bf16 v[102:105], v[170:173], v[232:235], v[102:105]
	v_mfma_f32_16x16x32_bf16 v[98:101], v[178:181], v[232:235], v[98:101]
	v_mfma_f32_16x16x32_bf16 v[86:89], v[170:173], v[240:243], v[86:89]
	v_mfma_f32_16x16x32_bf16 v[82:85], v[178:181], v[240:243], v[82:85]
	v_mfma_f32_16x16x32_bf16 v[70:73], v[170:173], v[248:251], v[70:73]
	v_mfma_f32_16x16x32_bf16 v[66:69], v[178:181], v[248:251], v[66:69]
	s_setprio 0
	s_barrier
; #define PG8_STAGE(bufoff, gbase, voff) do { _Pragma("unroll") for (int _i = 0; _i < 2; ++_i) \
;         __builtin_amdgcn_global_load_lds((const unsigned*)((const char*)(gbase) + (voff)[_i]), (LAS unsigned*)(lds + (bufoff) + ldsw + _i * 8192), 16, 0, 0); } while (0)
; #define PG8_LDA(dst, b, h) do { _Pragma("unroll") for (int m = 0; m < 4; ++m) _Pragma("unroll") for (int k = 0; k < 2; ++k) dst[m][k] = *(const LAS bf16x8*)(lds + PG8_SA(b, h) + aoff + m * 2048 + k * 1024); } while (0)
; #define PG8_MMA(ai, bj, At, Bt) do { __builtin_amdgcn_s_setprio(1); _Pragma("unroll") for (int m = 0; m < 4; ++m) _Pragma("unroll") for (int n = 0; n < 2; ++n) _Pragma("unroll") for (int k = 0; k < 2; ++k) \
;         acc[ai][bj][m][n] = __builtin_amdgcn_mfma_f32_16x16x32_bf16(Bt[n][k], At[m][k], acc[ai][bj][m][n], 0, 0, 0); __builtin_amdgcn_s_setprio(0); } while (0)
; #define PG8_WAIT_V(n) asm volatile("s_waitcnt vmcnt(" #n ")" ::: "memory")
; #define PG8_WAIT_L(n) asm volatile("s_waitcnt lgkmcnt(" #n ")" ::: "memory")
; #define PG8_BAR __builtin_amdgcn_s_barrier()
; #define PG8_SCHED __builtin_amdgcn_sched_barrier(0)
; #define PG8_STAGE(bufoff, gbase, voff, q64) do { \
;         __builtin_amdgcn_global_load_lds((const unsigned*)((const char*)(gbase) + (voff)), (LAS unsigned*)(lds + (bufoff) + ldsw), 16, 0, 0); \
;         __builtin_amdgcn_global_load_lds((const unsigned*)((const char*)(gbase) + (q64) + (voff)), (LAS unsigned*)(lds + (bufoff) + ldsw + 8192), 16, 0, 0); } while (0)
; #define PG8_LDA(dst, b, h) do { _Pragma("unroll") for (int m = 0; m < 4; ++m) _Pragma("unroll") for (int k = 0; k < 2; ++k) dst[m][k] = *(const LAS bf16x8*)(lds + PG8_SA(b, h) + aoff + m * 2048 + k * 1024); } while (0)
; #define PG8_WAIT_V(n) asm volatile("s_waitcnt vmcnt(" #n ")" ::: "memory")
; #define PG8_WAIT_L(n) asm volatile("s_waitcnt lgkmcnt(" #n ")" ::: "memory")
; #define PG8_BAR __builtin_amdgcn_s_barrier()
; template <class Epi, class Sched>
; __device__ __forceinline__ void gemm_phase(LAS unsigned char* lds, const Gemm g, const Sched S, const Epi E, const int tid) {
;     ...
;             PG8_LDA(At, 1, 1); PG8_STAGE(PG8_SB(1, 0), b3, voffB); PG8_STAGE(PG8_SB(1, 1), b3 + hstepB, voffB); PG8_STAGE(PG8_SA(1, 0), a3, voffA);
;             PG8_WAIT_V(8); PG8_WAIT_L(0); PG8_BAR; PG8_MMA(1, 0, At, B0); PG8_MMA(1, 1, At, B1); PG8_BAR; PG8_SCHED;
;         }
	s_add_i32 s28, s41, s15
	v_lshl_add_u64 v[190:191], v[190:191], 0, s[0:1]
	s_mov_b32 m0, s28
	ds_read_b128 v[182:185], v153 offset:49152
	ds_read_b128 v[186:189], v153 offset:50176
	ds_read_b128 v[206:209], v153 offset:51200
	ds_read_b128 v[232:235], v153 offset:52224
	ds_read_b128 v[236:239], v153 offset:53248
	ds_read_b128 v[240:243], v153 offset:54272
	ds_read_b128 v[244:247], v153 offset:55296
	ds_read_b128 v[248:251], v153 offset:56320
	global_load_lds_dwordx4 v[190:191], off
	v_lshl_add_u64 v[190:191], v[210:211], 0, s[0:1]
	s_add_i32 m0, s28, 0x2000
	s_add_i32 s28, s48, s15
	global_load_lds_dwordx4 v[190:191], off
	v_lshl_add_u64 v[190:191], v[218:219], 0, s[0:1]
	s_mov_b32 m0, s28
	s_nop 0
	global_load_lds_dwordx4 v[190:191], off
	v_lshl_add_u64 v[190:191], v[220:221], 0, s[0:1]
	s_add_i32 m0, s28, 0x2000
	s_nop 0
	global_load_lds_dwordx4 v[190:191], off
	v_lshl_add_u64 v[190:191], v[192:193], 0, s[0:1]
	s_mov_b32 m0, s35
	s_nop 0
	global_load_lds_dwordx4 v[190:191], off
	v_lshl_add_u64 v[190:191], v[222:223], 0, s[0:1]
	s_mov_b32 m0, s52
	s_nop 0
	global_load_lds_dwordx4 v[190:191], off
	s_waitcnt vmcnt(8)
	s_waitcnt lgkmcnt(0)
	s_barrier
	s_setprio 1
	s_waitcnt lgkmcnt(0)
	v_mfma_f32_16x16x32_bf16 v[62:65], v[148:151], v[182:185], v[62:65]
	v_mfma_f32_16x16x32_bf16 v[58:61], v[158:161], v[182:185], v[58:61]
	v_mfma_f32_16x16x32_bf16 v[46:49], v[148:151], v[206:209], v[46:49]
	v_mfma_f32_16x16x32_bf16 v[42:45], v[158:161], v[206:209], v[42:45]
	v_mfma_f32_16x16x32_bf16 v[30:33], v[148:151], v[236:239], v[30:33]
	v_mfma_f32_16x16x32_bf16 v[26:29], v[158:161], v[236:239], v[26:29]
	v_mfma_f32_16x16x32_bf16 v[14:17], v[148:151], v[244:247], v[14:17]
	v_mfma_f32_16x16x32_bf16 v[10:13], v[158:161], v[244:247], v[10:13]
	v_mfma_f32_16x16x32_bf16 v[62:65], v[154:157], v[186:189], v[62:65]
	v_mfma_f32_16x16x32_bf16 v[58:61], v[162:165], v[186:189], v[58:61]
	v_mfma_f32_16x16x32_bf16 v[46:49], v[154:157], v[232:235], v[46:49]
	v_mfma_f32_16x16x32_bf16 v[42:45], v[162:165], v[232:235], v[42:45]
	v_mfma_f32_16x16x32_bf16 v[30:33], v[154:157], v[240:243], v[30:33]
	v_mfma_f32_16x16x32_bf16 v[26:29], v[162:165], v[240:243], v[26:29]
	v_mfma_f32_16x16x32_bf16 v[14:17], v[154:157], v[248:251], v[14:17]
	v_mfma_f32_16x16x32_bf16 v[10:13], v[162:165], v[248:251], v[10:13]
	s_setprio 0
	s_setprio 1
	v_mfma_f32_16x16x32_bf16 v[54:57], v[166:169], v[182:185], v[54:57]
	v_mfma_f32_16x16x32_bf16 v[50:53], v[174:177], v[182:185], v[50:53]
	v_mfma_f32_16x16x32_bf16 v[38:41], v[166:169], v[206:209], v[38:41]
	v_mfma_f32_16x16x32_bf16 v[34:37], v[174:177], v[206:209], v[34:37]
	v_mfma_f32_16x16x32_bf16 v[22:25], v[166:169], v[236:239], v[22:25]
	v_mfma_f32_16x16x32_bf16 v[18:21], v[174:177], v[236:239], v[18:21]
	v_mfma_f32_16x16x32_bf16 v[6:9], v[166:169], v[244:247], v[6:9]
	v_mfma_f32_16x16x32_bf16 v[2:5], v[174:177], v[244:247], v[2:5]
	v_mfma_f32_16x16x32_bf16 v[54:57], v[170:173], v[186:189], v[54:57]
	v_mfma_f32_16x16x32_bf16 v[50:53], v[178:181], v[186:189], v[50:53]
	v_mfma_f32_16x16x32_bf16 v[38:41], v[170:173], v[232:235], v[38:41]
	v_mfma_f32_16x16x32_bf16 v[34:37], v[178:181], v[232:235], v[34:37]
	v_mfma_f32_16x16x32_bf16 v[22:25], v[170:173], v[240:243], v[22:25]
	v_mfma_f32_16x16x32_bf16 v[18:21], v[178:181], v[240:243], v[18:21]
	v_mfma_f32_16x16x32_bf16 v[6:9], v[170:173], v[248:251], v[6:9]
	v_mfma_f32_16x16x32_bf16 v[2:5], v[178:181], v[248:251], v[2:5]
	s_setprio 0
	s_barrier
	s_add_u32 s38, s38, 0x100
	s_addc_u32 s39, s39, 0
	s_add_u32 s24, s24, 0x100
	s_addc_u32 s25, s25, 0
	s_cmp_ge_i32 s40, s54
	s_mov_b32 s28, s40
	s_cbranch_scc1 .Lpl1100_exit

; template <class Epi, class Sched>
; __device__ __forceinline__ void gemm_phase(LAS unsigned char* lds, const Gemm g, const Sched S, const Epi E, const int tid) {
;     ...
;     f32x4 acc[2][2][4][2];
; #pragma unroll
;     for (int a = 0; a < 2; ++a)
; #pragma unroll
;         for (int b = 0; b < 2; ++b)
; #pragma unroll
;             for (int m = 0; m < 4; ++m)
; #pragma unroll
;                 for (int n = 0; n < 2; ++n) acc[a][b][m][n] = (f32x4){0.f, 0.f, 0.f, 0.f};
.Lpl1100_zero:
	v_mov_b32_e32 v125, 0
	v_mov_b32_e32 v124, v125
	v_mov_b32_e32 v123, v125
	v_mov_b32_e32 v122, v125
	v_mov_b32_e32 v129, v125
	v_mov_b32_e32 v128, v125
	v_mov_b32_e32 v127, v125
	v_mov_b32_e32 v126, v125
	v_mov_b32_e32 v113, v125
	v_mov_b32_e32 v112, v125
	v_mov_b32_e32 v111, v125
	v_mov_b32_e32 v110, v125
	v_mov_b32_e32 v109, v125
	v_mov_b32_e32 v108, v125
	v_mov_b32_e32 v107, v125
	v_mov_b32_e32 v106, v125
	v_mov_b32_e32 v97, v125
	v_mov_b32_e32 v96, v125
	v_mov_b32_e32 v95, v125
	v_mov_b32_e32 v94, v125
	v_mov_b32_e32 v93, v125
	v_mov_b32_e32 v92, v125
	v_mov_b32_e32 v91, v125
	v_mov_b32_e32 v90, v125
	v_mov_b32_e32 v81, v125
	v_mov_b32_e32 v80, v125
	v_mov_b32_e32 v79, v125
	v_mov_b32_e32 v78, v125
	v_mov_b32_e32 v77, v125
	v_mov_b32_e32 v76, v125
	v_mov_b32_e32 v75, v125
	v_mov_b32_e32 v74, v125
	v_mov_b32_e32 v121, v125
	v_mov_b32_e32 v120, v125
	v_mov_b32_e32 v119, v125
	v_mov_b32_e32 v118, v125
	v_mov_b32_e32 v117, v125
	v_mov_b32_e32 v116, v125
	v_mov_b32_e32 v115, v125
	v_mov_b32_e32 v114, v125
	v_mov_b32_e32 v105, v125
	v_mov_b32_e32 v104, v125
	v_mov_b32_e32 v103, v125
	v_mov_b32_e32 v102, v125
	v_mov_b32_e32 v101, v125
	v_mov_b32_e32 v100, v125
	v_mov_b32_e32 v99, v125
	v_mov_b32_e32 v98, v125
	v_mov_b32_e32 v89, v125
	v_mov_b32_e32 v88, v125
	v_mov_b32_e32 v87, v125
	v_mov_b32_e32 v86, v125
	v_mov_b32_e32 v85, v125
	v_mov_b32_e32 v84, v125
	v_mov_b32_e32 v83, v125
	v_mov_b32_e32 v82, v125
	v_mov_b32_e32 v73, v125
	v_mov_b32_e32 v72, v125
	v_mov_b32_e32 v71, v125
	v_mov_b32_e32 v70, v125
	v_mov_b32_e32 v69, v125
	v_mov_b32_e32 v68, v125
	v_mov_b32_e32 v67, v125
	v_mov_b32_e32 v66, v125
	v_mov_b32_e32 v65, v125
	v_mov_b32_e32 v64, v125
	v_mov_b32_e32 v63, v125
	v_mov_b32_e32 v62, v125
	v_mov_b32_e32 v61, v125
	v_mov_b32_e32 v60, v125
	v_mov_b32_e32 v59, v125
	v_mov_b32_e32 v58, v125
	v_mov_b32_e32 v49, v125
	v_mov_b32_e32 v48, v125
	v_mov_b32_e32 v47, v125
	v_mov_b32_e32 v46, v125
	v_mov_b32_e32 v45, v125
	v_mov_b32_e32 v44, v125
	v_mov_b32_e32 v43, v125
	v_mov_b32_e32 v42, v125
	v_mov_b32_e32 v33, v125
	v_mov_b32_e32 v32, v125
	v_mov_b32_e32 v31, v125
	v_mov_b32_e32 v30, v125
	v_mov_b32_e32 v29, v125
	v_mov_b32_e32 v28, v125
	v_mov_b32_e32 v27, v125
	v_mov_b32_e32 v26, v125
	v_mov_b32_e32 v17, v125
	v_mov_b32_e32 v16, v125
	v_mov_b32_e32 v15, v125
	v_mov_b32_e32 v14, v125
	v_mov_b32_e32 v13, v125
	v_mov_b32_e32 v12, v125
	v_mov_b32_e32 v11, v125
	v_mov_b32_e32 v10, v125
	v_mov_b32_e32 v57, v125
	v_mov_b32_e32 v56, v125
	v_mov_b32_e32 v55, v125
	v_mov_b32_e32 v54, v125
	v_mov_b32_e32 v53, v125
	v_mov_b32_e32 v52, v125
	v_mov_b32_e32 v51, v125
	v_mov_b32_e32 v50, v125
	v_mov_b32_e32 v41, v125
	v_mov_b32_e32 v40, v125
	v_mov_b32_e32 v39, v125
	v_mov_b32_e32 v38, v125
	v_mov_b32_e32 v37, v125
	v_mov_b32_e32 v36, v125
	v_mov_b32_e32 v35, v125
	v_mov_b32_e32 v34, v125
	v_mov_b32_e32 v25, v125
	v_mov_b32_e32 v24, v125
	v_mov_b32_e32 v23, v125
	v_mov_b32_e32 v22, v125
	v_mov_b32_e32 v21, v125
	v_mov_b32_e32 v20, v125
	v_mov_b32_e32 v19, v125
	v_mov_b32_e32 v18, v125
	v_mov_b32_e32 v9, v125
	v_mov_b32_e32 v8, v125
	v_mov_b32_e32 v7, v125
	v_mov_b32_e32 v6, v125
	v_mov_b32_e32 v5, v125
	v_mov_b32_e32 v4, v125
	v_mov_b32_e32 v3, v125
	v_mov_b32_e32 v2, v125
	s_branch .LBB0_1102
